# P11 epilogue: W_s fragments of row groups 1-3 staged in LDS by LDS-DMA from the peeled last k-iteration (static LDS +16 KB), biases loaded at the epilogue head, V^T chunk-0 + LN gamma/beta prefetched;
# speedup vs baseline: 1.0092x; 1.0092x over previous
; #define PG8_STAGE(bufoff, gbase, voff) do { _Pragma("unroll") for (int _i = 0; _i < 2; ++_i) \
;         __builtin_amdgcn_global_load_lds((const unsigned*)((const char*)(gbase) + (voff)[_i]), (PG8_LAS unsigned*)(lds + (bufoff) + ldsw + _i * 8192), 16, 0, 0); } while (0)
; #define PG8_LDA(dst, b, h) do { _Pragma("unroll") for (int m = 0; m < 4; ++m) _Pragma("unroll") for (int k = 0; k < 2; ++k) dst[m][k] = *(const PG8_LAS bf16x8*)(lds + PG8_SA(b, h) + aoff + m * 2048 + k * 1024); } while (0)
; #define PG8_LDB(dst, b, h) do { _Pragma("unroll") for (int n = 0; n < 2; ++n) _Pragma("unroll") for (int k = 0; k < 2; ++k) dst[n][k] = *(const PG8_LAS bf16x8*)(lds + PG8_SB(b, h) + boff + n * 2048 + k * 1024); } while (0)
; #define PG8_MMA(ai, bj, At, Bt) do { __builtin_amdgcn_s_setprio(1); _Pragma("unroll") for (int m = 0; m < 4; ++m) _Pragma("unroll") for (int n = 0; n < 2; ++n) _Pragma("unroll") for (int k = 0; k < 2; ++k) \
;         acc[ai][bj][m][n] = __builtin_amdgcn_mfma_f32_16x16x32_bf16(Bt[n][k], At[m][k], acc[ai][bj][m][n], 0, 0, 0); __builtin_amdgcn_s_setprio(0); } while (0)
; #define PG8_WAIT_V(n) asm volatile("s_waitcnt vmcnt(" #n ")" ::: "memory")
; #define PG8_WAIT_L(n) asm volatile("s_waitcnt lgkmcnt(" #n ")" ::: "memory")
; #define PG8_BAR __builtin_amdgcn_s_barrier()
; #define PG8_SCHED __builtin_amdgcn_sched_barrier(0)
; template <class Epi, class Sched, bool ALIGN_EPI = false, bool SP2 = false>
; __device__ __forceinline__ void gemm_phase(PG8_LAS unsigned char* lds, const Gemm g, const Sched& S, const Epi& E) {
;     ...
;             PG8_LDB(B0, 0, 0); PG8_LDB(B1, 0, 1); PG8_SCHED; PG8_LDA(At, 0, 0); PG8_STAGE(PG8_SA(1, 1), a1 + hstepA, voffA);
;             PG8_WAIT_V(8); PG8_WAIT_L(0); PG8_BAR; PG8_MMA(0, 0, At, B0); PG8_MMA(0, 1, At, B1); PG8_BAR; PG8_SCHED;
;             PG8_LDA(At, 0, 1); PG8_STAGE(PG8_SB(0, 0), b2, voffB); PG8_STAGE(PG8_SB(0, 1), b2 + hstepB, voffB); PG8_STAGE(PG8_SA(0, 0), a2, voffA);
;             PG8_WAIT_V(8); PG8_WAIT_L(0); PG8_BAR; PG8_MMA(1, 0, At, B0); PG8_MMA(1, 1, At, B1); PG8_BAR; PG8_SCHED;
.Lsp_LBB0_1127:
.LBB0_1127:
	ds_read_b128 v[130:133], v203
	ds_read_b128 v[134:137], v203 offset:1024
	ds_read_b128 v[138:141], v203 offset:2048
	ds_read_b128 v[142:145], v203 offset:3072
	ds_read_b128 v[146:149], v205
	ds_read_b128 v[150:153], v205 offset:1024
	ds_read_b128 v[154:157], v205 offset:2048
	ds_read_b128 v[158:161], v205 offset:3072
	s_add_u32 s34, s40, 0xfff00080
	s_addc_u32 s35, s41, -1
	s_cmp_eq_u32 s53, 60
	s_cselect_b32 s35, s25, s35
	s_cselect_b32 s34, s26, s34
	s_cselect_b32 s43, s23, s52
	s_cselect_b32 s42, s27, s45
	s_add_i32 m0, s47, 0xc000
	ds_read_b128 v[162:165], v207
	ds_read_b128 v[166:169], v207 offset:1024
	ds_read_b128 v[170:173], v207 offset:2048
	ds_read_b128 v[174:177], v207 offset:3072
	ds_read_b128 v[196:199], v207 offset:4096
	ds_read_b128 v[208:211], v207 offset:5120
	ds_read_b128 v[212:215], v207 offset:6144
	ds_read_b128 v[216:219], v207 offset:7168
	global_load_lds_dwordx4 v188, s[40:41]
	s_add_i32 m0, s47, 0xe000
	s_nop 0
	global_load_lds_dwordx4 v190, s[40:41]
	s_waitcnt vmcnt(8)
	s_waitcnt lgkmcnt(0)
	s_barrier
	s_waitcnt lgkmcnt(0)
	v_mfma_f32_16x16x32_bf16 v[122:125], v[130:133], v[162:165], v[122:125]
	v_mfma_f32_16x16x32_bf16 v[118:121], v[138:141], v[162:165], v[118:121]
	v_mfma_f32_16x16x32_bf16 v[106:109], v[130:133], v[170:173], v[106:109]
	v_mfma_f32_16x16x32_bf16 v[102:105], v[138:141], v[170:173], v[102:105]
	v_mfma_f32_16x16x32_bf16 v[90:93], v[130:133], v[196:199], v[90:93]
	v_mfma_f32_16x16x32_bf16 v[86:89], v[138:141], v[196:199], v[86:89]
	v_mfma_f32_16x16x32_bf16 v[74:77], v[130:133], v[212:215], v[74:77]
	v_mfma_f32_16x16x32_bf16 v[70:73], v[138:141], v[212:215], v[70:73]
	v_mfma_f32_16x16x32_bf16 v[122:125], v[134:137], v[166:169], v[122:125]
	v_mfma_f32_16x16x32_bf16 v[118:121], v[142:145], v[166:169], v[118:121]
	v_mfma_f32_16x16x32_bf16 v[106:109], v[134:137], v[174:177], v[106:109]
	v_mfma_f32_16x16x32_bf16 v[102:105], v[142:145], v[174:177], v[102:105]
	v_mfma_f32_16x16x32_bf16 v[90:93], v[134:137], v[208:211], v[90:93]
	v_mfma_f32_16x16x32_bf16 v[86:89], v[142:145], v[208:211], v[86:89]
	v_mfma_f32_16x16x32_bf16 v[74:77], v[134:137], v[216:219], v[74:77]
	v_mfma_f32_16x16x32_bf16 v[70:73], v[142:145], v[216:219], v[70:73]
	v_mfma_f32_16x16x32_bf16 v[126:129], v[146:149], v[162:165], v[126:129]
	v_mfma_f32_16x16x32_bf16 v[114:117], v[154:157], v[162:165], v[114:117]
	v_mfma_f32_16x16x32_bf16 v[110:113], v[146:149], v[170:173], v[110:113]
	v_mfma_f32_16x16x32_bf16 v[98:101], v[154:157], v[170:173], v[98:101]
	v_mfma_f32_16x16x32_bf16 v[94:97], v[146:149], v[196:199], v[94:97]
	v_mfma_f32_16x16x32_bf16 v[82:85], v[154:157], v[196:199], v[82:85]
	v_mfma_f32_16x16x32_bf16 v[78:81], v[146:149], v[212:215], v[78:81]
	v_mfma_f32_16x16x32_bf16 v[66:69], v[154:157], v[212:215], v[66:69]
	v_mfma_f32_16x16x32_bf16 v[126:129], v[150:153], v[166:169], v[126:129]
	v_mfma_f32_16x16x32_bf16 v[114:117], v[158:161], v[166:169], v[114:117]
	v_mfma_f32_16x16x32_bf16 v[110:113], v[150:153], v[174:177], v[110:113]
	v_mfma_f32_16x16x32_bf16 v[98:101], v[158:161], v[174:177], v[98:101]
	v_mfma_f32_16x16x32_bf16 v[94:97], v[150:153], v[208:211], v[94:97]
	v_mfma_f32_16x16x32_bf16 v[82:85], v[158:161], v[208:211], v[82:85]
	v_mfma_f32_16x16x32_bf16 v[78:81], v[150:153], v[216:219], v[78:81]
	v_mfma_f32_16x16x32_bf16 v[66:69], v[158:161], v[216:219], v[66:69]
	s_barrier
	s_add_i32 s73, s68, s17
	s_add_u32 s98, s42, 0x80
	s_addc_u32 s99, s43, 0
	s_add_u32 s100, s34, 0x80
	s_addc_u32 s101, s35, 0
	s_mov_b32 m0, s73
	ds_read_b128 v[162:165], v207 offset:16384
	ds_read_b128 v[166:169], v207 offset:17408
	ds_read_b128 v[170:173], v207 offset:18432
	ds_read_b128 v[174:177], v207 offset:19456
	ds_read_b128 v[196:199], v207 offset:20480
	ds_read_b128 v[208:211], v207 offset:21504
	ds_read_b128 v[212:215], v207 offset:22528
	ds_read_b128 v[216:219], v207 offset:23552
	global_load_lds_dwordx4 v182, s[42:43]
	s_add_i32 m0, s73, 0x2000
	s_add_u32 s74, s42, 0x100000
	s_addc_u32 s75, s43, 0
	s_add_i32 s73, s69, s17
	global_load_lds_dwordx4 v178, s[42:43]
	s_mov_b32 m0, s73
	s_nop 0
	global_load_lds_dwordx4 v182, s[74:75]
	s_add_i32 m0, s73, 0x2000
	s_nop 0
	global_load_lds_dwordx4 v178, s[74:75]
	s_mov_b32 m0, s47
	s_nop 0
	global_load_lds_dwordx4 v184, s[34:35]
	s_mov_b32 m0, s48
	s_nop 0
	global_load_lds_dwordx4 v180, s[34:35]
	s_waitcnt vmcnt(8)
	s_waitcnt lgkmcnt(0)
	s_barrier
	s_waitcnt lgkmcnt(0)
	v_mfma_f32_16x16x32_bf16 v[58:61], v[130:133], v[162:165], v[58:61]
	v_mfma_f32_16x16x32_bf16 v[54:57], v[138:141], v[162:165], v[54:57]
	v_mfma_f32_16x16x32_bf16 v[42:45], v[130:133], v[170:173], v[42:45]
	v_mfma_f32_16x16x32_bf16 v[38:41], v[138:141], v[170:173], v[38:41]
	v_mfma_f32_16x16x32_bf16 v[26:29], v[130:133], v[196:199], v[26:29]
	v_mfma_f32_16x16x32_bf16 v[22:25], v[138:141], v[196:199], v[22:25]
	v_mfma_f32_16x16x32_bf16 v[10:13], v[130:133], v[212:215], v[10:13]
	v_mfma_f32_16x16x32_bf16 v[6:9], v[138:141], v[212:215], v[6:9]
	v_mfma_f32_16x16x32_bf16 v[58:61], v[134:137], v[166:169], v[58:61]
	v_mfma_f32_16x16x32_bf16 v[54:57], v[142:145], v[166:169], v[54:57]
	v_mfma_f32_16x16x32_bf16 v[42:45], v[134:137], v[174:177], v[42:45]
	v_mfma_f32_16x16x32_bf16 v[38:41], v[142:145], v[174:177], v[38:41]
	v_mfma_f32_16x16x32_bf16 v[26:29], v[134:137], v[208:211], v[26:29]
	v_mfma_f32_16x16x32_bf16 v[22:25], v[142:145], v[208:211], v[22:25]
	v_mfma_f32_16x16x32_bf16 v[10:13], v[134:137], v[216:219], v[10:13]
	v_mfma_f32_16x16x32_bf16 v[6:9], v[142:145], v[216:219], v[6:9]
	v_mfma_f32_16x16x32_bf16 v[62:65], v[146:149], v[162:165], v[62:65]
	v_mfma_f32_16x16x32_bf16 v[50:53], v[154:157], v[162:165], v[50:53]
	v_mfma_f32_16x16x32_bf16 v[46:49], v[146:149], v[170:173], v[46:49]
	v_mfma_f32_16x16x32_bf16 v[34:37], v[154:157], v[170:173], v[34:37]
	v_mfma_f32_16x16x32_bf16 v[30:33], v[146:149], v[196:199], v[30:33]
	v_mfma_f32_16x16x32_bf16 v[18:21], v[154:157], v[196:199], v[18:21]
	v_mfma_f32_16x16x32_bf16 v[14:17], v[146:149], v[212:215], v[14:17]
	v_mfma_f32_16x16x32_bf16 v[2:5], v[154:157], v[212:215], v[2:5]
	v_mfma_f32_16x16x32_bf16 v[62:65], v[150:153], v[166:169], v[62:65]
	v_mfma_f32_16x16x32_bf16 v[50:53], v[158:161], v[166:169], v[50:53]
	v_mfma_f32_16x16x32_bf16 v[46:49], v[150:153], v[174:177], v[46:49]
	v_mfma_f32_16x16x32_bf16 v[34:37], v[158:161], v[174:177], v[34:37]
	v_mfma_f32_16x16x32_bf16 v[30:33], v[150:153], v[208:211], v[30:33]
	v_mfma_f32_16x16x32_bf16 v[18:21], v[158:161], v[208:211], v[18:21]
	v_mfma_f32_16x16x32_bf16 v[14:17], v[150:153], v[216:219], v[14:17]
	v_mfma_f32_16x16x32_bf16 v[2:5], v[158:161], v[216:219], v[2:5]
	s_barrier
; #define PG8_STAGE(bufoff, gbase, voff) do { _Pragma("unroll") for (int _i = 0; _i < 2; ++_i) \
;         __builtin_amdgcn_global_load_lds((const unsigned*)((const char*)(gbase) + (voff)[_i]), (PG8_LAS unsigned*)(lds + (bufoff) + ldsw + _i * 8192), 16, 0, 0); } while (0)
; #define PG8_LDA(dst, b, h) do { _Pragma("unroll") for (int m = 0; m < 4; ++m) _Pragma("unroll") for (int k = 0; k < 2; ++k) dst[m][k] = *(const PG8_LAS bf16x8*)(lds + PG8_SA(b, h) + aoff + m * 2048 + k * 1024); } while (0)
; #define PG8_LDB(dst, b, h) do { _Pragma("unroll") for (int n = 0; n < 2; ++n) _Pragma("unroll") for (int k = 0; k < 2; ++k) dst[n][k] = *(const PG8_LAS bf16x8*)(lds + PG8_SB(b, h) + boff + n * 2048 + k * 1024); } while (0)
; #define PG8_MMA(ai, bj, At, Bt) do { __builtin_amdgcn_s_setprio(1); _Pragma("unroll") for (int m = 0; m < 4; ++m) _Pragma("unroll") for (int n = 0; n < 2; ++n) _Pragma("unroll") for (int k = 0; k < 2; ++k) \
;         acc[ai][bj][m][n] = __builtin_amdgcn_mfma_f32_16x16x32_bf16(Bt[n][k], At[m][k], acc[ai][bj][m][n], 0, 0, 0); __builtin_amdgcn_s_setprio(0); } while (0)
; #define PG8_WAIT_V(n) asm volatile("s_waitcnt vmcnt(" #n ")" ::: "memory")
; #define PG8_WAIT_L(n) asm volatile("s_waitcnt lgkmcnt(" #n ")" ::: "memory")
; #define PG8_BAR __builtin_amdgcn_s_barrier()
; #define PG8_SCHED __builtin_amdgcn_sched_barrier(0)
; template <class Epi, class Sched, bool ALIGN_EPI = false, bool SP2 = false>
; __device__ __forceinline__ void gemm_phase(PG8_LAS unsigned char* lds, const Gemm g, const Sched& S, const Epi& E) {
;     ...
;             PG8_LDB(B0, 1, 0); PG8_LDB(B1, 1, 1); PG8_SCHED; PG8_LDA(At, 1, 0); PG8_STAGE(PG8_SA(0, 1), a2 + hstepA, voffA);
;             PG8_WAIT_V(8); PG8_WAIT_L(0); PG8_BAR; PG8_MMA(0, 0, At, B0); PG8_MMA(0, 1, At, B1); PG8_BAR; PG8_SCHED;
;             PG8_LDA(At, 1, 1); PG8_STAGE(PG8_SB(1, 0), b3, voffB); PG8_STAGE(PG8_SB(1, 1), b3 + hstepB, voffB); PG8_STAGE(PG8_SA(1, 0), a3, voffA);
;             PG8_WAIT_V(8); PG8_WAIT_L(0); PG8_BAR; PG8_MMA(1, 0, At, B0); PG8_MMA(1, 1, At, B1); PG8_BAR; PG8_SCHED;
	s_add_i32 s73, 0, 0x18000
	s_add_i32 s74, 0, 0x1c000
	v_add_u32_e32 v142, s73, v1
	v_add_u32_e32 v158, s74, v1
	ds_read_b128 v[130:133], v142
	ds_read_b128 v[134:137], v142 offset:1024
	ds_read_b128 v[138:141], v142 offset:2048
	ds_read_b128 v[142:145], v142 offset:3072
	ds_read_b128 v[146:149], v158
	ds_read_b128 v[150:153], v158 offset:1024
	ds_read_b128 v[154:157], v158 offset:2048
	ds_read_b128 v[158:161], v158 offset:3072
	s_add_u32 s34, s34, 0x100000
	s_addc_u32 s35, s35, 0
	s_mov_b32 m0, s49
	ds_read_b128 v[162:165], v207 offset:32768
	ds_read_b128 v[166:169], v207 offset:33792
	ds_read_b128 v[170:173], v207 offset:34816
	ds_read_b128 v[174:177], v207 offset:35840
	ds_read_b128 v[196:199], v207 offset:36864
	ds_read_b128 v[208:211], v207 offset:37888
	ds_read_b128 v[212:215], v207 offset:38912
	ds_read_b128 v[216:219], v207 offset:39936
	global_load_lds_dwordx4 v184, s[34:35]
	s_mov_b32 m0, s60
	s_nop 0
	global_load_lds_dwordx4 v180, s[34:35]
	s_waitcnt vmcnt(8)
	s_waitcnt lgkmcnt(0)
	s_barrier
	s_waitcnt lgkmcnt(0)
	v_mfma_f32_16x16x32_bf16 v[122:125], v[130:133], v[162:165], v[122:125]
	v_mfma_f32_16x16x32_bf16 v[118:121], v[138:141], v[162:165], v[118:121]
	v_mfma_f32_16x16x32_bf16 v[106:109], v[130:133], v[170:173], v[106:109]
	v_mfma_f32_16x16x32_bf16 v[102:105], v[138:141], v[170:173], v[102:105]
	v_mfma_f32_16x16x32_bf16 v[90:93], v[130:133], v[196:199], v[90:93]
	v_mfma_f32_16x16x32_bf16 v[86:89], v[138:141], v[196:199], v[86:89]
	v_mfma_f32_16x16x32_bf16 v[74:77], v[130:133], v[212:215], v[74:77]
	v_mfma_f32_16x16x32_bf16 v[70:73], v[138:141], v[212:215], v[70:73]
	v_mfma_f32_16x16x32_bf16 v[122:125], v[134:137], v[166:169], v[122:125]
	v_mfma_f32_16x16x32_bf16 v[118:121], v[142:145], v[166:169], v[118:121]
	v_mfma_f32_16x16x32_bf16 v[106:109], v[134:137], v[174:177], v[106:109]
	v_mfma_f32_16x16x32_bf16 v[102:105], v[142:145], v[174:177], v[102:105]
	v_mfma_f32_16x16x32_bf16 v[90:93], v[134:137], v[208:211], v[90:93]
	v_mfma_f32_16x16x32_bf16 v[86:89], v[142:145], v[208:211], v[86:89]
	v_mfma_f32_16x16x32_bf16 v[74:77], v[134:137], v[216:219], v[74:77]
	v_mfma_f32_16x16x32_bf16 v[70:73], v[142:145], v[216:219], v[70:73]
	v_mfma_f32_16x16x32_bf16 v[126:129], v[146:149], v[162:165], v[126:129]
	v_mfma_f32_16x16x32_bf16 v[114:117], v[154:157], v[162:165], v[114:117]
	v_mfma_f32_16x16x32_bf16 v[110:113], v[146:149], v[170:173], v[110:113]
	v_mfma_f32_16x16x32_bf16 v[98:101], v[154:157], v[170:173], v[98:101]
	v_mfma_f32_16x16x32_bf16 v[94:97], v[146:149], v[196:199], v[94:97]
	v_mfma_f32_16x16x32_bf16 v[82:85], v[154:157], v[196:199], v[82:85]
	v_mfma_f32_16x16x32_bf16 v[78:81], v[146:149], v[212:215], v[78:81]
	v_mfma_f32_16x16x32_bf16 v[66:69], v[154:157], v[212:215], v[66:69]
	v_mfma_f32_16x16x32_bf16 v[126:129], v[150:153], v[166:169], v[126:129]
	v_mfma_f32_16x16x32_bf16 v[114:117], v[158:161], v[166:169], v[114:117]
	v_mfma_f32_16x16x32_bf16 v[110:113], v[150:153], v[174:177], v[110:113]
	v_mfma_f32_16x16x32_bf16 v[98:101], v[158:161], v[174:177], v[98:101]
	v_mfma_f32_16x16x32_bf16 v[94:97], v[150:153], v[208:211], v[94:97]
	v_mfma_f32_16x16x32_bf16 v[82:85], v[158:161], v[208:211], v[82:85]
	v_mfma_f32_16x16x32_bf16 v[78:81], v[150:153], v[216:219], v[78:81]
	v_mfma_f32_16x16x32_bf16 v[66:69], v[158:161], v[216:219], v[66:69]
	s_barrier
	s_add_i32 s34, s73, s17
	s_mov_b32 m0, s34
	ds_read_b128 v[162:165], v207 offset:49152
	ds_read_b128 v[166:169], v207 offset:50176
	ds_read_b128 v[170:173], v207 offset:51200
	ds_read_b128 v[174:177], v207 offset:52224
	ds_read_b128 v[196:199], v207 offset:53248
	ds_read_b128 v[208:211], v207 offset:54272
	ds_read_b128 v[212:215], v207 offset:55296
	ds_read_b128 v[216:219], v207 offset:56320
	global_load_lds_dwordx4 v182, s[98:99]
	s_add_i32 m0, s34, 0x2000
	s_add_u32 s34, s42, 0x100080
	s_addc_u32 s35, s43, 0
	s_add_i32 s42, s74, s17
	global_load_lds_dwordx4 v178, s[98:99]
	s_mov_b32 m0, s42
	s_nop 0
	global_load_lds_dwordx4 v182, s[34:35]
	s_add_i32 m0, s42, 0x2000
	s_nop 0
	global_load_lds_dwordx4 v178, s[34:35]
	s_mov_b32 m0, s64
	s_nop 0
	global_load_lds_dwordx4 v184, s[100:101]
	s_mov_b32 m0, s65
	s_nop 0
	global_load_lds_dwordx4 v180, s[100:101]
	s_waitcnt vmcnt(8)
	s_waitcnt lgkmcnt(0)
	s_barrier
	s_waitcnt lgkmcnt(0)
	v_mfma_f32_16x16x32_bf16 v[58:61], v[130:133], v[162:165], v[58:61]
	v_mfma_f32_16x16x32_bf16 v[54:57], v[138:141], v[162:165], v[54:57]
	v_mfma_f32_16x16x32_bf16 v[42:45], v[130:133], v[170:173], v[42:45]
	v_mfma_f32_16x16x32_bf16 v[38:41], v[138:141], v[170:173], v[38:41]
	v_mfma_f32_16x16x32_bf16 v[26:29], v[130:133], v[196:199], v[26:29]
	v_mfma_f32_16x16x32_bf16 v[22:25], v[138:141], v[196:199], v[22:25]
	v_mfma_f32_16x16x32_bf16 v[10:13], v[130:133], v[212:215], v[10:13]
	v_mfma_f32_16x16x32_bf16 v[6:9], v[138:141], v[212:215], v[6:9]
	v_mfma_f32_16x16x32_bf16 v[58:61], v[134:137], v[166:169], v[58:61]
	v_mfma_f32_16x16x32_bf16 v[54:57], v[142:145], v[166:169], v[54:57]
	v_mfma_f32_16x16x32_bf16 v[42:45], v[134:137], v[174:177], v[42:45]
	v_mfma_f32_16x16x32_bf16 v[38:41], v[142:145], v[174:177], v[38:41]
	v_mfma_f32_16x16x32_bf16 v[26:29], v[134:137], v[208:211], v[26:29]
	v_mfma_f32_16x16x32_bf16 v[22:25], v[142:145], v[208:211], v[22:25]
	v_mfma_f32_16x16x32_bf16 v[10:13], v[134:137], v[216:219], v[10:13]
	v_mfma_f32_16x16x32_bf16 v[6:9], v[142:145], v[216:219], v[6:9]
	v_mfma_f32_16x16x32_bf16 v[62:65], v[146:149], v[162:165], v[62:65]
	v_mfma_f32_16x16x32_bf16 v[50:53], v[154:157], v[162:165], v[50:53]
	v_mfma_f32_16x16x32_bf16 v[46:49], v[146:149], v[170:173], v[46:49]
	v_mfma_f32_16x16x32_bf16 v[34:37], v[154:157], v[170:173], v[34:37]
	v_mfma_f32_16x16x32_bf16 v[30:33], v[146:149], v[196:199], v[30:33]
	v_mfma_f32_16x16x32_bf16 v[18:21], v[154:157], v[196:199], v[18:21]
	v_mfma_f32_16x16x32_bf16 v[14:17], v[146:149], v[212:215], v[14:17]
	v_mfma_f32_16x16x32_bf16 v[2:5], v[154:157], v[212:215], v[2:5]
	v_mfma_f32_16x16x32_bf16 v[62:65], v[150:153], v[166:169], v[62:65]
	v_mfma_f32_16x16x32_bf16 v[50:53], v[158:161], v[166:169], v[50:53]
	v_mfma_f32_16x16x32_bf16 v[46:49], v[150:153], v[174:177], v[46:49]
	v_mfma_f32_16x16x32_bf16 v[34:37], v[158:161], v[174:177], v[34:37]
	v_mfma_f32_16x16x32_bf16 v[30:33], v[150:153], v[208:211], v[30:33]
	v_mfma_f32_16x16x32_bf16 v[18:21], v[158:161], v[208:211], v[18:21]
	v_mfma_f32_16x16x32_bf16 v[14:17], v[150:153], v[216:219], v[14:17]
	v_mfma_f32_16x16x32_bf16 v[2:5], v[158:161], v[216:219], v[2:5]
	s_barrier
; template <class Epi, class Sched, bool ALIGN_EPI = false, bool SP2 = false>
; __device__ __forceinline__ void gemm_phase(PG8_LAS unsigned char* lds, const Gemm g, const Sched& S, const Epi& E) {
;     ...
;         for (int t = 0; t < nt; t += 2) {
;             const bool last = (t == nt - 2);
;             const char* a1 = cA + (size_t)(t + 1) * kstep;
;             const char* a2 = last ? nA : cA + (size_t)(t + 2) * kstep; const char* b2 = last ? nB : cB + (size_t)(t + 2) * kstep;
;             const char* a3 = a2 + kstep; const char* b3 = b2 + kstep;
;             if (last && has_next) S.a_ready(nxt);
;             if constexpr (SP2) {
;             PG8_LDB(B0, 0, 0); PG8_LDB(B1, 0, 1); PG8_SCHED; PG8_LDA(At, 0, 0); PG8_STAGE(PG8_SA(1, 1), a1 + hstepA, voffA);
;             PG8_WAIT_V(8); PG8_WAIT_L(0); PG8_BAR; PG8_MMA(0, 0, At, B0); PG8_MMA(0, 1, At, B1); PG8_BAR; PG8_SCHED;
;     __device__ __forceinline__ void operator()(const af4 (&acc)[2][2][4][2], const pg8::Unit& u, int wr_, int wc_, int fr_, int fq_) const {
;     ...
;         for (int n = 0; n < 2; ++n) { lg[n] = lng[chl + 4 * n]; lb[n] = lnb[chl + 4 * n]; }
;         v4u raw[2][4];
;         auto load_raw = [&](int ai) {
; #pragma unroll
;             for (int ks = 0; ks < 4; ++ks)
; #pragma unroll
;                 for (int n = 0; n < 2; ++n) raw[n][ks] = *(const GAS v4u*)(VT + (size_t)(chl + 4 * n) * MLAT + u.pm * 256 + ai * 128 + 32 * ks + 8 * fq);
;         };
;         load_raw(0);
; #pragma unroll
;         for (int ai = 0; ai < 2; ++ai) {
;             const int tok0 = u.pm * 256 + ai * 128;
;             bf16x8 av[2][4];
; #pragma unroll
;             for (int ks = 0; ks < 4; ++ks) {
;                 const int j0 = tok0 + 32 * ks + 8 * fq;
;                 f32x4 st[4];
; #pragma unroll
;                 for (int q = 0; q < 4; ++q) st[q] = *(const GAS f32x4*)(stats + (size_t)(j0 + 2 * q) * 2);
; #pragma unroll
;                 for (int n = 0; n < 2; ++n) {
;                     float vf[8];
;                     unpack8(raw[n][ks], vf);
; #pragma unroll
;                     for (int q = 0; q < 4; ++q) { f32x2 t = {vf[2 * q], vf[2 * q + 1]}; t = t * (f32x2){st[q].z, st[q].w} + (f32x2){st[q].x, st[q].y}; t = t * lg[n] + lb[n]; vf[2 * q] = t.x; vf[2 * q + 1] = t.y; }
;                     av[n][ks] = __builtin_bit_cast(bf16x8, pack8(vf));
;                 }
;             }
; #pragma unroll
	s_add_i32 s53, s53, 2
	s_add_u32 s40, s40, 0x100
	s_addc_u32 s41, s41, 0
	s_add_u32 s45, s45, 0x100
	s_addc_u32 s52, s52, 0
	s_cmp_gt_u32 s53, 59
	s_cbranch_scc0 .LBB0_1127
	ds_read_b128 v[130:133], v203
	ds_read_b128 v[134:137], v203 offset:1024
	ds_read_b128 v[138:141], v203 offset:2048
	ds_read_b128 v[142:145], v203 offset:3072
	ds_read_b128 v[146:149], v205
	ds_read_b128 v[150:153], v205 offset:1024
	ds_read_b128 v[154:157], v205 offset:2048
	ds_read_b128 v[158:161], v205 offset:3072
	s_add_u32 s34, s40, 0xfff00080
	s_addc_u32 s35, s41, -1
	s_cmp_eq_u32 s53, 60
	s_cselect_b32 s35, s25, s35
	s_cselect_b32 s34, s26, s34
	s_cselect_b32 s43, s23, s52
	s_cselect_b32 s42, s27, s45
	s_add_i32 m0, s47, 0xc000
	ds_read_b128 v[162:165], v207
	ds_read_b128 v[166:169], v207 offset:1024
	ds_read_b128 v[170:173], v207 offset:2048
	ds_read_b128 v[174:177], v207 offset:3072
	ds_read_b128 v[196:199], v207 offset:4096
	ds_read_b128 v[208:211], v207 offset:5120
	ds_read_b128 v[212:215], v207 offset:6144
	ds_read_b128 v[216:219], v207 offset:7168
	global_load_lds_dwordx4 v188, s[40:41]
	s_add_i32 m0, s47, 0xe000
	s_nop 0
	global_load_lds_dwordx4 v190, s[40:41]
	v_readlane_b32 s98, v254, 12
	v_readlane_b32 s99, v254, 13
	v_readlane_b32 s100, v254, 14
	v_readlane_b32 s101, v254, 15
	v_readfirstlane_b32 s73, v0
	v_lshlrev_b32_e32 v200, 1, v0
	v_and_b32_e32 v201, 3, v0
	v_and_b32_e32 v200, 24, v200
	s_lshl_b32 s74, s44, 7
	v_or3_b32 v200, v201, v200, s74
	s_lshr_b32 s74, s73, 1
	s_and_b32 s74, s74, 0x60
	v_or_b32_e32 v200, s74, v200
	v_lshlrev_b32_e32 v204, 2, v200
	v_lshrrev_b32_e32 v202, 1, v0
	v_and_b32_e32 v202, 24, v202
	v_lshlrev_b32_e32 v200, 15, v200
	v_lshl_add_u32 v200, v202, 1, v200
	s_lshl_b32 s74, s6, 9
	v_add_u32_e32 v200, s74, v200
	v_add_u32_e32 v201, 0x20000, v200
	v_and_b32_e32 v206, 0x100, v0
	v_and_b32_e32 v202, 15, v0
	v_lshlrev_b32_e32 v206, 6, v206
	v_lshl_or_b32 v206, v202, 8, v206
	v_and_b32_e32 v202, 0xf0, v0
	v_or_b32_e32 v206, v206, v202
	global_load_dword v179, v204, s[98:99]
	global_load_dword v181, v204, s[98:99] offset:16
	global_load_dword v183, v204, s[100:101]
	global_load_dword v185, v204, s[100:101] offset:16
	global_load_dwordx4 v[192:195], v200, s[50:51]
	global_load_dwordx4 v[222:225], v201, s[50:51]
	global_load_dwordx4 v[226:229], v200, s[50:51] offset:64
	global_load_dwordx4 v[234:237], v200, s[50:51] offset:128
	global_load_dwordx4 v[238:241], v200, s[50:51] offset:192
	global_load_dwordx4 v[242:245], v201, s[50:51] offset:64
	global_load_dwordx4 v[246:249], v201, s[50:51] offset:128
	global_load_dwordx4 v[250:253], v201, s[50:51] offset:192
	s_mul_hi_i32 s74, s44, 0x2aaaaaab
	s_lshl_b32 s74, s74, 15
	s_add_u32 s98, s62, s74
	s_addc_u32 s99, s63, 0
	s_mov_b32 s100, 0x20800
	s_mov_b32 s101, 0x24000
	s_bitcmp1_b32 s73, 8
	s_cselect_b32 s100, s101, s100
	s_and_b32 s74, s73, 0xc0
	s_lshl_b32 s74, s74, 4
	s_add_i32 s100, s100, s74
	s_add_u32 s98, s98, 0x1000
	s_addc_u32 s99, s99, 0
	s_add_i32 m0, s100, 0x0
	s_nop 0
	global_load_lds_dwordx4 v206, s[98:99]
	s_add_u32 s98, s98, 0x1000
	s_addc_u32 s99, s99, 0
	s_add_i32 m0, s100, 0x1000
	s_nop 0
	global_load_lds_dwordx4 v206, s[98:99]
	s_add_u32 s98, s98, 0x1000
	s_addc_u32 s99, s99, 0
	s_add_i32 m0, s100, 0x2000
	s_nop 0
	global_load_lds_dwordx4 v206, s[98:99]
	s_waitcnt vmcnt(23)
	s_waitcnt lgkmcnt(0)
	s_barrier
	s_waitcnt lgkmcnt(0)
	v_mfma_f32_16x16x32_bf16 v[122:125], v[130:133], v[162:165], v[122:125]
	v_mfma_f32_16x16x32_bf16 v[118:121], v[138:141], v[162:165], v[118:121]
	v_mfma_f32_16x16x32_bf16 v[106:109], v[130:133], v[170:173], v[106:109]
	v_mfma_f32_16x16x32_bf16 v[102:105], v[138:141], v[170:173], v[102:105]
	v_mfma_f32_16x16x32_bf16 v[90:93], v[130:133], v[196:199], v[90:93]
	v_mfma_f32_16x16x32_bf16 v[86:89], v[138:141], v[196:199], v[86:89]
	v_mfma_f32_16x16x32_bf16 v[74:77], v[130:133], v[212:215], v[74:77]
	v_mfma_f32_16x16x32_bf16 v[70:73], v[138:141], v[212:215], v[70:73]
	v_mfma_f32_16x16x32_bf16 v[122:125], v[134:137], v[166:169], v[122:125]
	v_mfma_f32_16x16x32_bf16 v[118:121], v[142:145], v[166:169], v[118:121]
	v_mfma_f32_16x16x32_bf16 v[106:109], v[134:137], v[174:177], v[106:109]
	v_mfma_f32_16x16x32_bf16 v[102:105], v[142:145], v[174:177], v[102:105]
	v_mfma_f32_16x16x32_bf16 v[90:93], v[134:137], v[208:211], v[90:93]
	v_mfma_f32_16x16x32_bf16 v[86:89], v[142:145], v[208:211], v[86:89]
	v_mfma_f32_16x16x32_bf16 v[74:77], v[134:137], v[216:219], v[74:77]
	v_mfma_f32_16x16x32_bf16 v[70:73], v[142:145], v[216:219], v[70:73]
	v_mfma_f32_16x16x32_bf16 v[126:129], v[146:149], v[162:165], v[126:129]
	v_mfma_f32_16x16x32_bf16 v[114:117], v[154:157], v[162:165], v[114:117]
	v_mfma_f32_16x16x32_bf16 v[110:113], v[146:149], v[170:173], v[110:113]
	v_mfma_f32_16x16x32_bf16 v[98:101], v[154:157], v[170:173], v[98:101]
	v_mfma_f32_16x16x32_bf16 v[94:97], v[146:149], v[196:199], v[94:97]
	v_mfma_f32_16x16x32_bf16 v[82:85], v[154:157], v[196:199], v[82:85]
	v_mfma_f32_16x16x32_bf16 v[78:81], v[146:149], v[212:215], v[78:81]
	v_mfma_f32_16x16x32_bf16 v[66:69], v[154:157], v[212:215], v[66:69]
	v_mfma_f32_16x16x32_bf16 v[126:129], v[150:153], v[166:169], v[126:129]
	v_mfma_f32_16x16x32_bf16 v[114:117], v[158:161], v[166:169], v[114:117]
	v_mfma_f32_16x16x32_bf16 v[110:113], v[150:153], v[174:177], v[110:113]
	v_mfma_f32_16x16x32_bf16 v[98:101], v[158:161], v[174:177], v[98:101]
	v_mfma_f32_16x16x32_bf16 v[94:97], v[150:153], v[208:211], v[94:97]
	v_mfma_f32_16x16x32_bf16 v[82:85], v[158:161], v[208:211], v[82:85]
	v_mfma_f32_16x16x32_bf16 v[78:81], v[150:153], v[216:219], v[78:81]
	v_mfma_f32_16x16x32_bf16 v[66:69], v[158:161], v[216:219], v[66:69]
	s_barrier
; #define PG8_STAGE(bufoff, gbase, voff) do { _Pragma("unroll") for (int _i = 0; _i < 2; ++_i) \
;         __builtin_amdgcn_global_load_lds((const unsigned*)((const char*)(gbase) + (voff)[_i]), (PG8_LAS unsigned*)(lds + (bufoff) + ldsw + _i * 8192), 16, 0, 0); } while (0)
; #define PG8_LDA(dst, b, h) do { _Pragma("unroll") for (int m = 0; m < 4; ++m) _Pragma("unroll") for (int k = 0; k < 2; ++k) dst[m][k] = *(const PG8_LAS bf16x8*)(lds + PG8_SA(b, h) + aoff + m * 2048 + k * 1024); } while (0)
; #define PG8_LDB(dst, b, h) do { _Pragma("unroll") for (int n = 0; n < 2; ++n) _Pragma("unroll") for (int k = 0; k < 2; ++k) dst[n][k] = *(const PG8_LAS bf16x8*)(lds + PG8_SB(b, h) + boff + n * 2048 + k * 1024); } while (0)
; #define PG8_MMA(ai, bj, At, Bt) do { __builtin_amdgcn_s_setprio(1); _Pragma("unroll") for (int m = 0; m < 4; ++m) _Pragma("unroll") for (int n = 0; n < 2; ++n) _Pragma("unroll") for (int k = 0; k < 2; ++k) \
;         acc[ai][bj][m][n] = __builtin_amdgcn_mfma_f32_16x16x32_bf16(Bt[n][k], At[m][k], acc[ai][bj][m][n], 0, 0, 0); __builtin_amdgcn_s_setprio(0); } while (0)
; #define PG8_WAIT_V(n) asm volatile("s_waitcnt vmcnt(" #n ")" ::: "memory")
; #define PG8_WAIT_L(n) asm volatile("s_waitcnt lgkmcnt(" #n ")" ::: "memory")
; #define PG8_BAR __builtin_amdgcn_s_barrier()
; #define PG8_SCHED __builtin_amdgcn_sched_barrier(0)
; template <class Epi, class Sched, bool ALIGN_EPI = false, bool SP2 = false>
; __device__ __forceinline__ void gemm_phase(PG8_LAS unsigned char* lds, const Gemm g, const Sched& S, const Epi& E) {
;     ...
;             PG8_LDA(At, 0, 1); PG8_STAGE(PG8_SB(0, 0), b2, voffB); PG8_STAGE(PG8_SB(0, 1), b2 + hstepB, voffB); PG8_STAGE(PG8_SA(0, 0), a2, voffA);
;             PG8_WAIT_V(8); PG8_WAIT_L(0); PG8_BAR; PG8_MMA(1, 0, At, B0); PG8_MMA(1, 1, At, B1); PG8_BAR; PG8_SCHED;
;             PG8_LDB(B0, 1, 0); PG8_LDB(B1, 1, 1); PG8_SCHED; PG8_LDA(At, 1, 0); PG8_STAGE(PG8_SA(0, 1), a2 + hstepA, voffA);
;             PG8_WAIT_V(8); PG8_WAIT_L(0); PG8_BAR; PG8_MMA(0, 0, At, B0); PG8_MMA(0, 1, At, B1); PG8_BAR; PG8_SCHED;
	s_add_i32 s73, s68, s17
	s_add_u32 s98, s42, 0x80
	s_addc_u32 s99, s43, 0
	s_add_u32 s100, s34, 0x80
	s_addc_u32 s101, s35, 0
	s_mov_b32 m0, s73
	ds_read_b128 v[162:165], v207 offset:16384
	ds_read_b128 v[166:169], v207 offset:17408
	ds_read_b128 v[170:173], v207 offset:18432
	ds_read_b128 v[174:177], v207 offset:19456
	ds_read_b128 v[196:199], v207 offset:20480
	ds_read_b128 v[208:211], v207 offset:21504
	ds_read_b128 v[212:215], v207 offset:22528
	ds_read_b128 v[216:219], v207 offset:23552
	global_load_lds_dwordx4 v182, s[42:43]
	s_add_i32 m0, s73, 0x2000
	s_add_u32 s74, s42, 0x100000
	s_addc_u32 s75, s43, 0
	s_add_i32 s73, s69, s17
	global_load_lds_dwordx4 v178, s[42:43]
	s_mov_b32 m0, s73
	s_nop 0
	global_load_lds_dwordx4 v182, s[74:75]
	s_add_i32 m0, s73, 0x2000
	s_nop 0
	global_load_lds_dwordx4 v178, s[74:75]
	s_mov_b32 m0, s47
	s_nop 0
	global_load_lds_dwordx4 v184, s[34:35]
	s_mov_b32 m0, s48
	s_nop 0
	global_load_lds_dwordx4 v180, s[34:35]
	s_waitcnt vmcnt(23)
	s_waitcnt lgkmcnt(0)
	s_barrier
	s_waitcnt lgkmcnt(0)
	v_mfma_f32_16x16x32_bf16 v[58:61], v[130:133], v[162:165], v[58:61]
	v_mfma_f32_16x16x32_bf16 v[54:57], v[138:141], v[162:165], v[54:57]
	v_mfma_f32_16x16x32_bf16 v[42:45], v[130:133], v[170:173], v[42:45]
	v_mfma_f32_16x16x32_bf16 v[38:41], v[138:141], v[170:173], v[38:41]
	v_mfma_f32_16x16x32_bf16 v[26:29], v[130:133], v[196:199], v[26:29]
	v_mfma_f32_16x16x32_bf16 v[22:25], v[138:141], v[196:199], v[22:25]
	v_mfma_f32_16x16x32_bf16 v[10:13], v[130:133], v[212:215], v[10:13]
	v_mfma_f32_16x16x32_bf16 v[6:9], v[138:141], v[212:215], v[6:9]
	v_mfma_f32_16x16x32_bf16 v[58:61], v[134:137], v[166:169], v[58:61]
	v_mfma_f32_16x16x32_bf16 v[54:57], v[142:145], v[166:169], v[54:57]
	v_mfma_f32_16x16x32_bf16 v[42:45], v[134:137], v[174:177], v[42:45]
	v_mfma_f32_16x16x32_bf16 v[38:41], v[142:145], v[174:177], v[38:41]
	v_mfma_f32_16x16x32_bf16 v[26:29], v[134:137], v[208:211], v[26:29]
	v_mfma_f32_16x16x32_bf16 v[22:25], v[142:145], v[208:211], v[22:25]
	v_mfma_f32_16x16x32_bf16 v[10:13], v[134:137], v[216:219], v[10:13]
	v_mfma_f32_16x16x32_bf16 v[6:9], v[142:145], v[216:219], v[6:9]
	v_mfma_f32_16x16x32_bf16 v[62:65], v[146:149], v[162:165], v[62:65]
	v_mfma_f32_16x16x32_bf16 v[50:53], v[154:157], v[162:165], v[50:53]
	v_mfma_f32_16x16x32_bf16 v[46:49], v[146:149], v[170:173], v[46:49]
	v_mfma_f32_16x16x32_bf16 v[34:37], v[154:157], v[170:173], v[34:37]
	v_mfma_f32_16x16x32_bf16 v[30:33], v[146:149], v[196:199], v[30:33]
	v_mfma_f32_16x16x32_bf16 v[18:21], v[154:157], v[196:199], v[18:21]
	v_mfma_f32_16x16x32_bf16 v[14:17], v[146:149], v[212:215], v[14:17]
	v_mfma_f32_16x16x32_bf16 v[2:5], v[154:157], v[212:215], v[2:5]
	v_mfma_f32_16x16x32_bf16 v[62:65], v[150:153], v[166:169], v[62:65]
	v_mfma_f32_16x16x32_bf16 v[50:53], v[158:161], v[166:169], v[50:53]
	v_mfma_f32_16x16x32_bf16 v[46:49], v[150:153], v[174:177], v[46:49]
	v_mfma_f32_16x16x32_bf16 v[34:37], v[158:161], v[174:177], v[34:37]
	v_mfma_f32_16x16x32_bf16 v[30:33], v[150:153], v[208:211], v[30:33]
	v_mfma_f32_16x16x32_bf16 v[18:21], v[158:161], v[208:211], v[18:21]
	v_mfma_f32_16x16x32_bf16 v[14:17], v[150:153], v[216:219], v[14:17]
	v_mfma_f32_16x16x32_bf16 v[2:5], v[158:161], v[216:219], v[2:5]
	s_barrier
	s_add_i32 s73, 0, 0x18000
	s_add_i32 s74, 0, 0x1c000
	v_add_u32_e32 v142, s73, v1
	v_add_u32_e32 v158, s74, v1
	ds_read_b128 v[130:133], v142
	ds_read_b128 v[134:137], v142 offset:1024
	ds_read_b128 v[138:141], v142 offset:2048
	ds_read_b128 v[142:145], v142 offset:3072
	ds_read_b128 v[146:149], v158
	ds_read_b128 v[150:153], v158 offset:1024
	ds_read_b128 v[154:157], v158 offset:2048
	ds_read_b128 v[158:161], v158 offset:3072
	s_add_u32 s34, s34, 0x100000
	s_addc_u32 s35, s35, 0
	s_mov_b32 m0, s49
	ds_read_b128 v[162:165], v207 offset:32768
	ds_read_b128 v[166:169], v207 offset:33792
	ds_read_b128 v[170:173], v207 offset:34816
	ds_read_b128 v[174:177], v207 offset:35840
	ds_read_b128 v[196:199], v207 offset:36864
	ds_read_b128 v[208:211], v207 offset:37888
	ds_read_b128 v[212:215], v207 offset:38912
	ds_read_b128 v[216:219], v207 offset:39936
	global_load_lds_dwordx4 v184, s[34:35]
	s_mov_b32 m0, s60
	s_nop 0
	global_load_lds_dwordx4 v180, s[34:35]
	s_waitcnt vmcnt(23)
	s_waitcnt lgkmcnt(0)
	s_barrier
; #define PG8_STAGE(bufoff, gbase, voff) do { _Pragma("unroll") for (int _i = 0; _i < 2; ++_i) \
;         __builtin_amdgcn_global_load_lds((const unsigned*)((const char*)(gbase) + (voff)[_i]), (PG8_LAS unsigned*)(lds + (bufoff) + ldsw + _i * 8192), 16, 0, 0); } while (0)
; #define PG8_LDA(dst, b, h) do { _Pragma("unroll") for (int m = 0; m < 4; ++m) _Pragma("unroll") for (int k = 0; k < 2; ++k) dst[m][k] = *(const PG8_LAS bf16x8*)(lds + PG8_SA(b, h) + aoff + m * 2048 + k * 1024); } while (0)
; #define PG8_MMA(ai, bj, At, Bt) do { __builtin_amdgcn_s_setprio(1); _Pragma("unroll") for (int m = 0; m < 4; ++m) _Pragma("unroll") for (int n = 0; n < 2; ++n) _Pragma("unroll") for (int k = 0; k < 2; ++k) \
;         acc[ai][bj][m][n] = __builtin_amdgcn_mfma_f32_16x16x32_bf16(Bt[n][k], At[m][k], acc[ai][bj][m][n], 0, 0, 0); __builtin_amdgcn_s_setprio(0); } while (0)
; #define PG8_WAIT_V(n) asm volatile("s_waitcnt vmcnt(" #n ")" ::: "memory")
; #define PG8_WAIT_L(n) asm volatile("s_waitcnt lgkmcnt(" #n ")" ::: "memory")
; #define PG8_BAR __builtin_amdgcn_s_barrier()
; #define PG8_SCHED __builtin_amdgcn_sched_barrier(0)
; template <class Epi, class Sched, bool ALIGN_EPI = false, bool SP2 = false>
; __device__ __forceinline__ void gemm_phase(PG8_LAS unsigned char* lds, const Gemm g, const Sched& S, const Epi& E) {
;     ...
;             PG8_WAIT_V(8); PG8_WAIT_L(0); PG8_BAR; PG8_MMA(0, 0, At, B0); PG8_MMA(0, 1, At, B1); PG8_BAR; PG8_SCHED;
;             PG8_LDA(At, 1, 1); PG8_STAGE(PG8_SB(1, 0), b3, voffB); PG8_STAGE(PG8_SB(1, 1), b3 + hstepB, voffB); PG8_STAGE(PG8_SA(1, 0), a3, voffA);
;             PG8_WAIT_V(8); PG8_WAIT_L(0); PG8_BAR; PG8_MMA(1, 0, At, B0); PG8_MMA(1, 1, At, B1); PG8_BAR; PG8_SCHED;
;     ...
;         if constexpr (ALIGN_EPI) { if (wr == 0) PG8_BAR; }
	s_waitcnt lgkmcnt(0)
	v_mfma_f32_16x16x32_bf16 v[122:125], v[130:133], v[162:165], v[122:125]
	v_mfma_f32_16x16x32_bf16 v[118:121], v[138:141], v[162:165], v[118:121]
	v_mfma_f32_16x16x32_bf16 v[106:109], v[130:133], v[170:173], v[106:109]
	v_mfma_f32_16x16x32_bf16 v[102:105], v[138:141], v[170:173], v[102:105]
	v_mfma_f32_16x16x32_bf16 v[90:93], v[130:133], v[196:199], v[90:93]
	v_mfma_f32_16x16x32_bf16 v[86:89], v[138:141], v[196:199], v[86:89]
	v_mfma_f32_16x16x32_bf16 v[74:77], v[130:133], v[212:215], v[74:77]
	v_mfma_f32_16x16x32_bf16 v[70:73], v[138:141], v[212:215], v[70:73]
	v_mfma_f32_16x16x32_bf16 v[122:125], v[134:137], v[166:169], v[122:125]
	v_mfma_f32_16x16x32_bf16 v[118:121], v[142:145], v[166:169], v[118:121]
	v_mfma_f32_16x16x32_bf16 v[106:109], v[134:137], v[174:177], v[106:109]
	v_mfma_f32_16x16x32_bf16 v[102:105], v[142:145], v[174:177], v[102:105]
	v_mfma_f32_16x16x32_bf16 v[90:93], v[134:137], v[208:211], v[90:93]
	v_mfma_f32_16x16x32_bf16 v[86:89], v[142:145], v[208:211], v[86:89]
	v_mfma_f32_16x16x32_bf16 v[74:77], v[134:137], v[216:219], v[74:77]
	v_mfma_f32_16x16x32_bf16 v[70:73], v[142:145], v[216:219], v[70:73]
	v_mfma_f32_16x16x32_bf16 v[126:129], v[146:149], v[162:165], v[126:129]
	v_mfma_f32_16x16x32_bf16 v[114:117], v[154:157], v[162:165], v[114:117]
	v_mfma_f32_16x16x32_bf16 v[110:113], v[146:149], v[170:173], v[110:113]
	v_mfma_f32_16x16x32_bf16 v[98:101], v[154:157], v[170:173], v[98:101]
	v_mfma_f32_16x16x32_bf16 v[94:97], v[146:149], v[196:199], v[94:97]
	v_mfma_f32_16x16x32_bf16 v[82:85], v[154:157], v[196:199], v[82:85]
	v_mfma_f32_16x16x32_bf16 v[78:81], v[146:149], v[212:215], v[78:81]
	v_mfma_f32_16x16x32_bf16 v[66:69], v[154:157], v[212:215], v[66:69]
	v_mfma_f32_16x16x32_bf16 v[126:129], v[150:153], v[166:169], v[126:129]
	v_mfma_f32_16x16x32_bf16 v[114:117], v[158:161], v[166:169], v[114:117]
	v_mfma_f32_16x16x32_bf16 v[110:113], v[150:153], v[174:177], v[110:113]
	v_mfma_f32_16x16x32_bf16 v[98:101], v[158:161], v[174:177], v[98:101]
	v_mfma_f32_16x16x32_bf16 v[94:97], v[150:153], v[208:211], v[94:97]
	v_mfma_f32_16x16x32_bf16 v[82:85], v[158:161], v[208:211], v[82:85]
	v_mfma_f32_16x16x32_bf16 v[78:81], v[150:153], v[216:219], v[78:81]
	v_mfma_f32_16x16x32_bf16 v[66:69], v[158:161], v[216:219], v[66:69]
	s_barrier
	s_add_i32 s34, s73, s17
	s_mov_b32 m0, s34
	ds_read_b128 v[162:165], v207 offset:49152
	ds_read_b128 v[166:169], v207 offset:50176
	ds_read_b128 v[170:173], v207 offset:51200
	ds_read_b128 v[174:177], v207 offset:52224
	ds_read_b128 v[196:199], v207 offset:53248
	ds_read_b128 v[208:211], v207 offset:54272
	ds_read_b128 v[212:215], v207 offset:55296
	ds_read_b128 v[216:219], v207 offset:56320
	global_load_lds_dwordx4 v182, s[98:99]
	s_add_i32 m0, s34, 0x2000
	s_add_u32 s34, s42, 0x100080
	s_addc_u32 s35, s43, 0
	s_add_i32 s42, s74, s17
	global_load_lds_dwordx4 v178, s[98:99]
	s_mov_b32 m0, s42
	s_nop 0
	global_load_lds_dwordx4 v182, s[34:35]
	s_add_i32 m0, s42, 0x2000
	s_nop 0
	global_load_lds_dwordx4 v178, s[34:35]
	s_mov_b32 m0, s64
	s_nop 0
	global_load_lds_dwordx4 v184, s[100:101]
	s_mov_b32 m0, s65
	s_nop 0
	global_load_lds_dwordx4 v180, s[100:101]
	s_waitcnt vmcnt(8)
	s_waitcnt lgkmcnt(0)
	s_barrier
	s_waitcnt lgkmcnt(0)
	v_mfma_f32_16x16x32_bf16 v[58:61], v[130:133], v[162:165], v[58:61]
	v_mfma_f32_16x16x32_bf16 v[54:57], v[138:141], v[162:165], v[54:57]
	v_mfma_f32_16x16x32_bf16 v[42:45], v[130:133], v[170:173], v[42:45]
	v_mfma_f32_16x16x32_bf16 v[38:41], v[138:141], v[170:173], v[38:41]
	v_mfma_f32_16x16x32_bf16 v[26:29], v[130:133], v[196:199], v[26:29]
	v_mfma_f32_16x16x32_bf16 v[22:25], v[138:141], v[196:199], v[22:25]
	v_mfma_f32_16x16x32_bf16 v[10:13], v[130:133], v[212:215], v[10:13]
	v_mfma_f32_16x16x32_bf16 v[6:9], v[138:141], v[212:215], v[6:9]
	v_mfma_f32_16x16x32_bf16 v[58:61], v[134:137], v[166:169], v[58:61]
	v_mfma_f32_16x16x32_bf16 v[54:57], v[142:145], v[166:169], v[54:57]
	v_mfma_f32_16x16x32_bf16 v[42:45], v[134:137], v[174:177], v[42:45]
	v_mfma_f32_16x16x32_bf16 v[38:41], v[142:145], v[174:177], v[38:41]
	v_mfma_f32_16x16x32_bf16 v[26:29], v[134:137], v[208:211], v[26:29]
	v_mfma_f32_16x16x32_bf16 v[22:25], v[142:145], v[208:211], v[22:25]
	v_mfma_f32_16x16x32_bf16 v[10:13], v[134:137], v[216:219], v[10:13]
	v_mfma_f32_16x16x32_bf16 v[6:9], v[142:145], v[216:219], v[6:9]
	v_mfma_f32_16x16x32_bf16 v[62:65], v[146:149], v[162:165], v[62:65]
	v_mfma_f32_16x16x32_bf16 v[50:53], v[154:157], v[162:165], v[50:53]
	v_mfma_f32_16x16x32_bf16 v[46:49], v[146:149], v[170:173], v[46:49]
	v_mfma_f32_16x16x32_bf16 v[34:37], v[154:157], v[170:173], v[34:37]
	v_mfma_f32_16x16x32_bf16 v[30:33], v[146:149], v[196:199], v[30:33]
	v_mfma_f32_16x16x32_bf16 v[18:21], v[154:157], v[196:199], v[18:21]
	v_mfma_f32_16x16x32_bf16 v[14:17], v[146:149], v[212:215], v[14:17]
	v_mfma_f32_16x16x32_bf16 v[2:5], v[154:157], v[212:215], v[2:5]
	v_mfma_f32_16x16x32_bf16 v[62:65], v[150:153], v[166:169], v[62:65]
	v_mfma_f32_16x16x32_bf16 v[50:53], v[158:161], v[166:169], v[50:53]
	v_mfma_f32_16x16x32_bf16 v[46:49], v[150:153], v[174:177], v[46:49]
	v_mfma_f32_16x16x32_bf16 v[34:37], v[158:161], v[174:177], v[34:37]
	v_mfma_f32_16x16x32_bf16 v[30:33], v[150:153], v[208:211], v[30:33]
	v_mfma_f32_16x16x32_bf16 v[18:21], v[158:161], v[208:211], v[18:21]
	v_mfma_f32_16x16x32_bf16 v[14:17], v[150:153], v[216:219], v[14:17]
	v_mfma_f32_16x16x32_bf16 v[2:5], v[158:161], v[216:219], v[2:5]
	s_barrier
	s_add_i32 s53, s53, 2
	s_add_u32 s40, s40, 0x100
	s_addc_u32 s41, s41, 0
	s_add_u32 s45, s45, 0x100
	s_addc_u32 s52, s52, 0
	s_setprio 0
	s_and_b64 vcc, exec, s[14:15]
	s_cbranch_vccz .LBB0_1130
	s_barrier

; #define GAS __attribute__((address_space(1)))
; __device__ __forceinline__ int my_tid() { int t = threadIdx.x; asm volatile("" : "+v"(t)); return t; }
;     __device__ __forceinline__ void operator()(const af4 (&acc)[2][2][4][2], const pg8::Unit& u, int wr_, int wc_, int fr_, int fq_) const {
;         const int tid = my_tid(), lane = tid & 63, wid = __builtin_amdgcn_readfirstlane(tid >> 6), wr = wid >> 2, wc = wid & 3, fr = lane & 15, fq = lane >> 4;
;         (void)wr_; (void)wc_; (void)fr_; (void)fq_;
;         const int chbase = u.pn * 128, grp = u.pn / 6;
;         const bf16* wsg = wsb + (size_t)grp * 128 * 128;
;         const int chl = chbase + 32 * wc + 8 * (fr >> 2) + (fr & 3);
;         float lg[2], lb[2];
; #pragma unroll
;         for (int n = 0; n < 2; ++n) { lg[n] = lng[chl + 4 * n]; lb[n] = lnb[chl + 4 * n]; }
;         v4u raw[2][4];
;         auto load_raw = [&](int ai) {
; #pragma unroll
;             for (int ks = 0; ks < 4; ++ks)
; #pragma unroll
;                 for (int n = 0; n < 2; ++n) raw[n][ks] = *(const GAS v4u*)(VT + (size_t)(chl + 4 * n) * MLAT + u.pm * 256 + ai * 128 + 32 * ks + 8 * fq);
;         };
;         load_raw(0);
;     ...
;                 const float bsi = bs[grp * 128 + it];
.Lp11_st_nowr:
	s_waitcnt lgkmcnt(0)
	s_barrier
	v_mov_b32_e32 v164, v0
	s_mul_hi_i32 s23, s44, 0x2aaaaaab
	s_lshr_b32 s26, s23, 31
	v_readfirstlane_b32 s25, v164
	v_lshlrev_b32_e32 v130, 1, v164
	s_lshl_b32 s40, s44, 7
	s_add_i32 s44, s23, s26
	s_lshr_b32 s23, s25, 1
	v_and_b32_e32 v130, 24, v130
	v_and_b32_e32 v131, 3, v164
	s_ashr_i32 s45, s44, 31
	s_and_b32 s23, s23, 0x60
	v_or3_b32 v130, v131, v130, s40
	s_lshl_b64 s[26:27], s[44:45], 15
	v_or_b32_e32 v146, s23, v130
	v_or_b32_e32 v134, 4, v146
	s_add_u32 s52, s62, s26
	v_ashrrev_i32_e32 v147, 31, v146
	v_ashrrev_i32_e32 v135, 31, v134
	s_addc_u32 s53, s63, s27
	s_lshl_b32 s42, s6, 8
	v_lshrrev_b32_e32 v132, 1, v164
	v_lshlrev_b64 v[130:131], 15, v[146:147]
	s_ashr_i32 s43, s42, 31
	v_and_b32_e32 v209, 24, v132
	v_lshlrev_b64 v[134:135], 15, v[134:135]
	v_lshl_add_u64 v[130:131], s[50:51], 0, v[130:131]
	s_lshl_b64 s[26:27], s[42:43], 1
	v_lshl_add_u64 v[134:135], s[50:51], 0, v[134:135]
	v_or_b32_e32 v162, s42, v209
	v_lshl_add_u64 v[130:131], v[130:131], 0, s[26:27]
	v_lshlrev_b32_e32 v186, 1, v209
	v_lshl_add_u64 v[148:149], v[134:135], 0, s[26:27]
	v_ashrrev_i32_e32 v163, 31, v162
	v_lshl_add_u64 v[216:217], v[130:131], 0, v[186:187]
	v_lshl_add_u32 v150, v162, 3, s98
	v_lshl_add_u64 v[220:221], v[148:149], 0, v[186:187]
	v_mov_b64_e32 v[130:131], v[192:193]
	v_mov_b64_e32 v[132:133], v[194:195]
	ds_read_b128 v[134:137], v150 offset:16
	ds_read_b128 v[138:141], v150
	ds_read_b128 v[142:145], v150 offset:48
	ds_read_b128 v[166:169], v150 offset:32
	v_mov_b64_e32 v[170:171], v[222:223]
	v_mov_b64_e32 v[172:173], v[224:225]
	v_readlane_b32 s80, v254, 2
	v_readlane_b32 s81, v254, 3
	v_readlane_b32 s90, v254, 12
	v_readlane_b32 s91, v254, 13
	v_readlane_b32 s92, v254, 14
	v_readlane_b32 s93, v254, 15
	v_lshlrev_b64 v[146:147], 2, v[146:147]
	s_mov_b64 s[78:79], s[90:91]
	s_mov_b64 s[80:81], s[92:93]
	v_lshl_add_u64 v[148:149], s[78:79], 0, v[146:147]
	v_lshl_add_u64 v[146:147], s[80:81], 0, v[146:147]
	v_mov_b32_e32 v206, v183
	v_mov_b32_e32 v208, v179
	v_mov_b32_e32 v202, v181
	v_mov_b32_e32 v204, v185
	s_mov_b32 s100, 0x20800
	s_mov_b32 s101, 0x24000
	s_bitcmp1_b32 s25, 8
	s_cselect_b32 s100, s101, s100
	v_and_b32_e32 v189, 63, v0
	v_lshl_add_u32 v189, v189, 4, s100
	s_lshr_b32 s99, s25, 2
	s_andn2_b32 s99, s99, 63
	v_and_or_b32 v185, v0, 15, s99
	v_lshl_add_u32 v185, s44, 7, v185
	v_lshlrev_b32_e32 v185, 2, v185
	global_load_dword v179, v185, s[76:77] offset:64
	global_load_dword v181, v185, s[76:77] offset:128
	global_load_dword v183, v185, s[76:77] offset:192
	v_mov_b64_e32 v[174:175], v[226:227]
	v_mov_b64_e32 v[176:177], v[228:229]
	v_mov_b64_e32 v[150:151], v[234:235]
	v_mov_b64_e32 v[152:153], v[236:237]
	v_mov_b64_e32 v[158:159], v[238:239]
	v_mov_b64_e32 v[160:161], v[240:241]
	v_mov_b64_e32 v[196:197], v[242:243]
	v_mov_b64_e32 v[198:199], v[244:245]
	s_nop 0
	v_mov_b64_e32 v[146:147], v[246:247]
	v_mov_b64_e32 v[148:149], v[248:249]
	v_mov_b64_e32 v[154:155], v[250:251]
	v_mov_b64_e32 v[156:157], v[252:253]
	s_ashr_i32 s6, s25, 2
	s_andn2_b32 s6, s6, 63
	v_pk_mul_f32 v[226:227], v[126:127], s[20:21] op_sel_hi:[1,0]
	v_pk_mul_f32 v[234:235], v[122:123], v[126:127]
	v_pk_mul_f32 v[126:127], v[128:129], s[20:21] op_sel_hi:[1,0]
	v_pk_mul_f32 v[236:237], v[124:125], v[128:129]
	v_pk_mul_f32 v[128:129], v[120:121], v[120:121]
	v_pk_mul_f32 v[228:229], v[118:119], v[118:119]
	v_pk_mul_f32 v[230:231], v[114:115], s[20:21] op_sel_hi:[1,0]
	v_pk_mul_f32 v[238:239], v[118:119], v[114:115]
	v_pk_mul_f32 v[114:115], v[116:117], s[20:21] op_sel_hi:[1,0]
	v_pk_mul_f32 v[240:241], v[120:121], v[116:117]
	v_exp_f32_e32 v126, v126
	v_exp_f32_e32 v127, v127
	v_exp_f32_e32 v114, v114
	v_exp_f32_e32 v115, v115
	s_ashr_i32 s41, s40, 31
	v_pk_add_f32 v[126:127], v[126:127], 1.0 op_sel_hi:[1,0]
	s_lshl_b64 s[40:41], s[40:41], 1
	v_pk_add_f32 v[114:115], v[114:115], 1.0 op_sel_hi:[1,0]
	v_pk_mul_f32 v[252:253], v[102:103], v[98:99]
	v_pk_mul_f32 v[192:193], v[104:105], v[100:101]
	s_andn2_b64 vcc, exec, s[4:5]
	v_readlane_b32 s82, v254, 4
	v_readlane_b32 s83, v254, 5
	v_readlane_b32 s84, v254, 6
	v_readlane_b32 s85, v254, 7
	v_readlane_b32 s86, v254, 8
	v_readlane_b32 s87, v254, 9
	v_readlane_b32 s88, v254, 10
	v_readlane_b32 s89, v254, 11
	v_readlane_b32 s94, v254, 16
	v_readlane_b32 s95, v254, 17
	s_waitcnt vmcnt(8)
	s_waitcnt lgkmcnt(0)
; #define GAS __attribute__((address_space(1)))
; __device__ __forceinline__ void unpack8(const v4u w, float (&f)[8]) { f[0] = bflo(w.x); f[1] = bfhi(w.x); f[2] = bflo(w.y); f[3] = bfhi(w.y); f[4] = bflo(w.z); f[5] = bfhi(w.z); f[6] = bflo(w.w); f[7] = bfhi(w.w); }
; __device__ __forceinline__ v4u pack8(const float (&f)[8]) { v4u w; w.x = pk2(f[0], f[1]); w.y = pk2(f[2], f[3]); w.z = pk2(f[4], f[5]); w.w = pk2(f[6], f[7]); return w; }
;     __device__ __forceinline__ void operator()(const af4 (&acc)[2][2][4][2], const pg8::Unit& u, int wr_, int wc_, int fr_, int fq_) const {
;     ...
; #pragma unroll
;         for (int ai = 0; ai < 2; ++ai) {
;             const int tok0 = u.pm * 256 + ai * 128;
;             bf16x8 av[2][4];
; #pragma unroll
;             for (int ks = 0; ks < 4; ++ks) {
;                 const int j0 = tok0 + 32 * ks + 8 * fq;
;                 f32x4 st[4];
; #pragma unroll
;                 for (int q = 0; q < 4; ++q) st[q] = *(const GAS f32x4*)(stats + (size_t)(j0 + 2 * q) * 2);
; #pragma unroll
;                 for (int n = 0; n < 2; ++n) {
;                     float vf[8];
;                     unpack8(raw[n][ks], vf);
; #pragma unroll
;                     for (int q = 0; q < 4; ++q) { f32x2 t = {vf[2 * q], vf[2 * q + 1]}; t = t * (f32x2){st[q].z, st[q].w} + (f32x2){st[q].x, st[q].y}; t = t * lg[n] + lb[n]; vf[2 * q] = t.x; vf[2 * q + 1] = t.y; }
;                     av[n][ks] = __builtin_bit_cast(bf16x8, pack8(vf));
;                 }
;             }
	v_lshlrev_b32_e32 v200, 16, v130
	v_and_b32_e32 v201, 0xffff0000, v130
	v_lshlrev_b32_e32 v212, 16, v170
	v_and_b32_e32 v213, 0xffff0000, v170
	v_lshlrev_b32_e32 v130, 16, v131
	v_and_b32_e32 v131, 0xffff0000, v131
	v_lshlrev_b32_e32 v210, 16, v132
	v_and_b32_e32 v211, 0xffff0000, v132
	v_lshlrev_b32_e32 v132, 16, v133
	v_and_b32_e32 v133, 0xffff0000, v133
	v_pk_fma_f32 v[200:201], v[140:141], v[200:201], v[138:139]
	v_lshlrev_b32_e32 v170, 16, v171
	v_and_b32_e32 v171, 0xffff0000, v171
	v_pk_fma_f32 v[138:139], v[140:141], v[212:213], v[138:139]
	v_pk_fma_f32 v[130:131], v[136:137], v[130:131], v[134:135]
	v_pk_fma_f32 v[210:211], v[168:169], v[210:211], v[166:167]
	v_pk_fma_f32 v[132:133], v[144:145], v[132:133], v[142:143]
	v_lshlrev_b32_e32 v214, 16, v172
	v_and_b32_e32 v215, 0xffff0000, v172
	v_lshlrev_b32_e32 v172, 16, v173
	v_and_b32_e32 v173, 0xffff0000, v173
	v_pk_fma_f32 v[134:135], v[136:137], v[170:171], v[134:135]
	v_pk_fma_f32 v[138:139], v[202:203], v[138:139], v[204:205] op_sel_hi:[0,1,0]
	v_pk_fma_f32 v[200:201], v[208:209], v[200:201], v[206:207] op_sel_hi:[0,1,0]
	v_pk_fma_f32 v[218:219], v[208:209], v[130:131], v[206:207] op_sel_hi:[0,1,0]
	v_pk_fma_f32 v[210:211], v[208:209], v[210:211], v[206:207] op_sel_hi:[0,1,0]
	v_pk_fma_f32 v[222:223], v[208:209], v[132:133], v[206:207] op_sel_hi:[0,1,0]
	v_pk_fma_f32 v[140:141], v[144:145], v[172:173], v[142:143]
	v_cvt_pk_bf16_f32 v130, v200, v201
	v_cvt_pk_bf16_f32 v131, v218, v219
	v_cvt_pk_bf16_f32 v132, v210, v211
	v_cvt_pk_bf16_f32 v133, v222, v223
	v_pk_fma_f32 v[142:143], v[202:203], v[134:135], v[204:205] op_sel_hi:[0,1,0]
	v_cvt_pk_bf16_f32 v134, v138, v139
	v_or_b32_e32 v138, 32, v162
	v_pk_fma_f32 v[136:137], v[168:169], v[214:215], v[166:167]
	v_ashrrev_i32_e32 v139, 31, v138
	v_pk_fma_f32 v[136:137], v[202:203], v[136:137], v[204:205] op_sel_hi:[0,1,0]
	v_pk_fma_f32 v[140:141], v[202:203], v[140:141], v[204:205] op_sel_hi:[0,1,0]
	v_lshl_add_u32 v170, v138, 3, s98
	v_cvt_pk_bf16_f32 v135, v142, v143
	v_cvt_pk_bf16_f32 v136, v136, v137
	v_cvt_pk_bf16_f32 v137, v140, v141
	ds_read_b128 v[138:141], v170
	ds_read_b128 v[142:145], v170 offset:16
	ds_read_b128 v[166:169], v170 offset:32
	s_nop 0
	ds_read_b128 v[170:173], v170 offset:48
	v_or_b32_e32 v200, 64, v162
	v_lshlrev_b32_e32 v210, 16, v174
	v_and_b32_e32 v211, 0xffff0000, v174
	v_lshlrev_b32_e32 v174, 16, v175
	v_and_b32_e32 v175, 0xffff0000, v175
	v_lshlrev_b32_e32 v212, 16, v176
	v_and_b32_e32 v213, 0xffff0000, v176
	v_lshlrev_b32_e32 v176, 16, v177
	v_and_b32_e32 v177, 0xffff0000, v177
	v_lshlrev_b32_e32 v214, 16, v196
	v_and_b32_e32 v215, 0xffff0000, v196
	v_lshlrev_b32_e32 v196, 16, v197
	v_and_b32_e32 v197, 0xffff0000, v197
	v_lshlrev_b32_e32 v218, 16, v198
	v_and_b32_e32 v219, 0xffff0000, v198
	v_lshlrev_b32_e32 v198, 16, v199
	v_and_b32_e32 v199, 0xffff0000, v199
	v_ashrrev_i32_e32 v201, 31, v200
	v_lshl_add_u32 v200, v200, 3, s98
	v_or_b32_e32 v162, 0x60, v162
	v_ashrrev_i32_e32 v163, 31, v162
	v_lshl_add_u32 v162, v162, 3, s98
	v_and_b32_e32 v165, 0xffff0000, v160
	s_waitcnt lgkmcnt(3)
	v_pk_fma_f32 v[210:211], v[140:141], v[210:211], v[138:139]
	s_waitcnt lgkmcnt(2)
	v_pk_fma_f32 v[174:175], v[144:145], v[174:175], v[142:143]
	s_waitcnt lgkmcnt(1)
	v_pk_fma_f32 v[212:213], v[168:169], v[212:213], v[166:167]
	s_waitcnt lgkmcnt(0)
	v_pk_fma_f32 v[176:177], v[172:173], v[176:177], v[170:171]
	v_pk_fma_f32 v[138:139], v[140:141], v[214:215], v[138:139]
	v_pk_fma_f32 v[140:141], v[144:145], v[196:197], v[142:143]
	v_pk_fma_f32 v[142:143], v[168:169], v[218:219], v[166:167]
	v_pk_fma_f32 v[144:145], v[172:173], v[198:199], v[170:171]
	v_pk_fma_f32 v[166:167], v[208:209], v[210:211], v[206:207] op_sel_hi:[0,1,0]
	v_pk_fma_f32 v[168:169], v[208:209], v[174:175], v[206:207] op_sel_hi:[0,1,0]
	v_pk_fma_f32 v[170:171], v[208:209], v[212:213], v[206:207] op_sel_hi:[0,1,0]
	v_pk_fma_f32 v[172:173], v[208:209], v[176:177], v[206:207] op_sel_hi:[0,1,0]
	v_pk_fma_f32 v[138:139], v[202:203], v[138:139], v[204:205] op_sel_hi:[0,1,0]
	v_pk_fma_f32 v[140:141], v[202:203], v[140:141], v[204:205] op_sel_hi:[0,1,0]
	v_pk_fma_f32 v[174:175], v[202:203], v[142:143], v[204:205] op_sel_hi:[0,1,0]
	v_pk_fma_f32 v[176:177], v[202:203], v[144:145], v[204:205] op_sel_hi:[0,1,0]
	v_cvt_pk_bf16_f32 v142, v166, v167
	v_cvt_pk_bf16_f32 v143, v168, v169
	v_cvt_pk_bf16_f32 v144, v170, v171
	v_cvt_pk_bf16_f32 v145, v172, v173
	v_cvt_pk_bf16_f32 v138, v138, v139
	v_cvt_pk_bf16_f32 v139, v140, v141
	v_cvt_pk_bf16_f32 v140, v174, v175
	v_cvt_pk_bf16_f32 v141, v176, v177
	ds_read_b128 v[166:169], v200
	ds_read_b128 v[170:173], v200 offset:16
	ds_read_b128 v[174:177], v200 offset:32
	ds_read_b128 v[196:199], v200 offset:48
	v_lshlrev_b32_e32 v200, 16, v150
	v_and_b32_e32 v201, 0xffff0000, v150
	v_lshlrev_b32_e32 v150, 16, v151
	v_and_b32_e32 v151, 0xffff0000, v151
	v_lshlrev_b32_e32 v210, 16, v152
	v_and_b32_e32 v211, 0xffff0000, v152
	v_lshlrev_b32_e32 v152, 16, v153
	v_and_b32_e32 v153, 0xffff0000, v153
	v_lshlrev_b32_e32 v212, 16, v146
	v_and_b32_e32 v213, 0xffff0000, v146
	v_lshlrev_b32_e32 v146, 16, v147
	v_and_b32_e32 v147, 0xffff0000, v147
	v_lshlrev_b32_e32 v214, 16, v148
	v_and_b32_e32 v215, 0xffff0000, v148
	v_lshlrev_b32_e32 v148, 16, v149
	v_and_b32_e32 v149, 0xffff0000, v149
	v_lshl_add_u64 v[218:219], s[52:53], 0, v[186:187]
	s_waitcnt lgkmcnt(3)
	v_pk_fma_f32 v[200:201], v[168:169], v[200:201], v[166:167]
	s_waitcnt lgkmcnt(2)
	v_pk_fma_f32 v[150:151], v[172:173], v[150:151], v[170:171]
	s_waitcnt lgkmcnt(1)
	v_pk_fma_f32 v[210:211], v[176:177], v[210:211], v[174:175]
	s_waitcnt lgkmcnt(0)
; #define GAS __attribute__((address_space(1)))
; __device__ __forceinline__ void unpack8(const v4u w, float (&f)[8]) { f[0] = bflo(w.x); f[1] = bfhi(w.x); f[2] = bflo(w.y); f[3] = bfhi(w.y); f[4] = bflo(w.z); f[5] = bfhi(w.z); f[6] = bflo(w.w); f[7] = bfhi(w.w); }
;     __device__ __forceinline__ void operator()(const af4 (&acc)[2][2][4][2], const pg8::Unit& u, int wr_, int wc_, int fr_, int fq_) const {
;     ...
;                 for (int n = 0; n < 2; ++n) {
;                     float vf[8];
;                     unpack8(raw[n][ks], vf);
; #pragma unroll
;                     for (int q = 0; q < 4; ++q) { f32x2 t = {vf[2 * q], vf[2 * q + 1]}; t = t * (f32x2){st[q].z, st[q].w} + (f32x2){st[q].x, st[q].y}; t = t * lg[n] + lb[n]; vf[2 * q] = t.x; vf[2 * q + 1] = t.y; }
;                     av[n][ks] = __builtin_bit_cast(bf16x8, pack8(vf));
;                 }
;             }
; #pragma unroll
;             for (int m = 0; m < 4; ++m) {
;                 if (ai == 0 && m == 0) load_raw(1);
;                 const int it = wr * 64 + m * 16 + fr;
;                 bf16x8 wf[4];
; #pragma unroll
;                 for (int ks = 0; ks < 4; ++ks) wf[ks] = *(const GAS bf16x8*)(wsg + (size_t)it * 128 + 32 * ks + 8 * fq);
;                 const float bsi = bs[grp * 128 + it];
;                 af4 vm[2] = {(af4){bsi, bsi, bsi, bsi}, (af4){bsi, bsi, bsi, bsi}};
; #pragma unroll
;                 for (int ks = 0; ks < 4; ++ks) {
; #pragma unroll
;                     for (int n = 0; n < 2; ++n) vm[n] = __builtin_amdgcn_mfma_f32_16x16x32_bf16(av[n][ks], wf[ks], vm[n], 0, 0, 0);
;                 }
;                 float o[8];
; #pragma unroll
;                 for (int n = 0; n < 2; ++n)
; #pragma unroll
;                     for (int e = 0; e < 4; e += 2) {
;                         const f32x2 uu = {acc[ai][0][m][n][e], acc[ai][0][m][n][e + 1]}, gg = {acc[ai][1][m][n][e], acc[ai][1][m][n][e + 1]}, vv = {vm[n][e], vm[n][e + 1]};
;                         const f32x2 ar = uu * (uu * uu * (-2.302208198f * 0.044715f) + (-2.302208198f));
;                         const f32x2 gs = gg * (-1.4426950408889634f);
;                         const f32x2 ea = {fexp2(ar.x), fexp2(ar.y)}, eb = {fexp2(gs.x), fexp2(gs.y)};
;                         const f32x2 q = eb + 1.0f, den = ea * q + q;
;                         const f32x2 r = {frcp(den.x), frcp(den.y)};
	v_pk_fma_f32 v[152:153], v[198:199], v[152:153], v[196:197]
	v_pk_fma_f32 v[166:167], v[168:169], v[212:213], v[166:167]
	v_pk_fma_f32 v[146:147], v[172:173], v[146:147], v[170:171]
	v_pk_fma_f32 v[168:169], v[176:177], v[214:215], v[174:175]
	v_pk_fma_f32 v[148:149], v[198:199], v[148:149], v[196:197]
	v_pk_fma_f32 v[170:171], v[208:209], v[200:201], v[206:207] op_sel_hi:[0,1,0]
	v_pk_fma_f32 v[172:173], v[208:209], v[150:151], v[206:207] op_sel_hi:[0,1,0]
	v_pk_fma_f32 v[174:175], v[208:209], v[210:211], v[206:207] op_sel_hi:[0,1,0]
	v_pk_fma_f32 v[176:177], v[208:209], v[152:153], v[206:207] op_sel_hi:[0,1,0]
	v_pk_fma_f32 v[166:167], v[202:203], v[166:167], v[204:205] op_sel_hi:[0,1,0]
	v_pk_fma_f32 v[196:197], v[202:203], v[146:147], v[204:205] op_sel_hi:[0,1,0]
	v_pk_fma_f32 v[168:169], v[202:203], v[168:169], v[204:205] op_sel_hi:[0,1,0]
	v_pk_fma_f32 v[198:199], v[202:203], v[148:149], v[204:205] op_sel_hi:[0,1,0]
	v_cvt_pk_bf16_f32 v150, v170, v171
	v_cvt_pk_bf16_f32 v151, v172, v173
	v_cvt_pk_bf16_f32 v152, v174, v175
	v_cvt_pk_bf16_f32 v153, v176, v177
	v_cvt_pk_bf16_f32 v146, v166, v167
	v_cvt_pk_bf16_f32 v147, v196, v197
	v_cvt_pk_bf16_f32 v148, v168, v169
	v_cvt_pk_bf16_f32 v149, v198, v199
	ds_read_b128 v[166:169], v162
	ds_read_b128 v[170:173], v162 offset:16
	ds_read_b128 v[174:177], v162 offset:32
	ds_read_b128 v[196:199], v162 offset:48
	v_and_or_b32 v210, v164, 15, s6
	v_lshl_add_u32 v162, s44, 7, v210
	v_ashrrev_i32_e32 v163, 31, v162
	v_lshl_add_u64 v[200:201], v[162:163], 2, s[76:77]
	v_lshlrev_b32_e32 v162, 16, v158
	v_and_b32_e32 v163, 0xffff0000, v158
	v_lshlrev_b32_e32 v164, 16, v160
	v_lshlrev_b32_e32 v212, 16, v154
	v_and_b32_e32 v213, 0xffff0000, v154
	v_lshlrev_b32_e32 v154, 16, v155
	v_and_b32_e32 v155, 0xffff0000, v155
	v_lshlrev_b32_e32 v158, 16, v159
	v_and_b32_e32 v159, 0xffff0000, v159
	v_lshlrev_b32_e32 v160, 16, v161
	v_and_b32_e32 v161, 0xffff0000, v161
	v_lshlrev_b32_e32 v214, 16, v156
	v_and_b32_e32 v215, 0xffff0000, v156
	v_lshlrev_b32_e32 v156, 16, v157
	v_and_b32_e32 v157, 0xffff0000, v157
	v_ashrrev_i32_e32 v211, 31, v210
	s_lshl_b32 s6, s23, 1
	s_or_b32 s23, s42, 0x80
	s_waitcnt lgkmcnt(3)
	v_pk_fma_f32 v[162:163], v[168:169], v[162:163], v[166:167]
	s_waitcnt lgkmcnt(2)
	v_pk_fma_f32 v[154:155], v[172:173], v[154:155], v[170:171]
	s_waitcnt lgkmcnt(1)
	v_pk_fma_f32 v[164:165], v[176:177], v[164:165], v[174:175]
	v_pk_fma_f32 v[158:159], v[172:173], v[158:159], v[170:171]
	s_waitcnt lgkmcnt(0)
	v_pk_fma_f32 v[160:161], v[198:199], v[160:161], v[196:197]
	v_pk_fma_f32 v[166:167], v[168:169], v[212:213], v[166:167]
	v_pk_fma_f32 v[168:169], v[176:177], v[214:215], v[174:175]
	v_pk_fma_f32 v[156:157], v[198:199], v[156:157], v[196:197]
	v_pk_fma_f32 v[162:163], v[208:209], v[162:163], v[206:207] op_sel_hi:[0,1,0]
	v_pk_fma_f32 v[164:165], v[208:209], v[164:165], v[206:207] op_sel_hi:[0,1,0]
	v_pk_fma_f32 v[154:155], v[202:203], v[154:155], v[204:205] op_sel_hi:[0,1,0]
	v_pk_fma_f32 v[158:159], v[208:209], v[158:159], v[206:207] op_sel_hi:[0,1,0]
	v_pk_fma_f32 v[160:161], v[208:209], v[160:161], v[206:207] op_sel_hi:[0,1,0]
	v_pk_fma_f32 v[170:171], v[202:203], v[166:167], v[204:205] op_sel_hi:[0,1,0]
	v_pk_fma_f32 v[172:173], v[202:203], v[168:169], v[204:205] op_sel_hi:[0,1,0]
	v_pk_fma_f32 v[156:157], v[202:203], v[156:157], v[204:205] op_sel_hi:[0,1,0]
	v_cvt_pk_bf16_f32 v166, v162, v163
	v_cvt_pk_bf16_f32 v167, v158, v159
	v_cvt_pk_bf16_f32 v168, v164, v165
	v_cvt_pk_bf16_f32 v169, v160, v161
	v_cvt_pk_bf16_f32 v162, v170, v171
	v_cvt_pk_bf16_f32 v163, v154, v155
	v_cvt_pk_bf16_f32 v164, v172, v173
	v_cvt_pk_bf16_f32 v165, v156, v157
	global_load_dword v154, v[200:201], off
	v_lshlrev_b64 v[156:157], 8, v[210:211]
	v_lshl_add_u64 v[214:215], v[218:219], 0, v[156:157]
	global_load_dwordx4 v[158:161], v[214:215], off
	global_load_dwordx4 v[170:173], v[214:215], off offset:64
	global_load_dwordx4 v[174:177], v[214:215], off offset:128
	global_load_dwordx4 v[222:225], v[214:215], off offset:192
	v_pk_mul_f32 v[156:157], v[124:125], v[124:125]
	v_pk_mul_f32 v[212:213], v[122:123], v[122:123]
	v_mov_b64_e32 v[196:197], s[18:19]
	v_pk_fma_f32 v[116:117], v[212:213], s[16:17], v[196:197] op_sel_hi:[1,0,0] neg_lo:[1,0,0] neg_hi:[1,0,0]
	v_exp_f32_e32 v212, v226
	v_exp_f32_e32 v213, v227
	v_pk_fma_f32 v[156:157], v[156:157], s[16:17], v[196:197] op_sel_hi:[1,0,0] neg_lo:[1,0,0] neg_hi:[1,0,0]
	v_pk_fma_f32 v[226:227], v[228:229], s[16:17], v[196:197] op_sel_hi:[1,0,0] neg_lo:[1,0,0] neg_hi:[1,0,0]
	v_pk_fma_f32 v[128:129], v[128:129], s[16:17], v[196:197] op_sel_hi:[1,0,0] neg_lo:[1,0,0] neg_hi:[1,0,0]
	v_exp_f32_e32 v228, v230
	v_exp_f32_e32 v229, v231
	v_pk_mul_f32 v[116:117], v[122:123], v[116:117]
	v_pk_mul_f32 v[122:123], v[124:125], v[156:157]
	v_pk_mul_f32 v[118:119], v[118:119], v[226:227]
	v_pk_mul_f32 v[120:121], v[120:121], v[128:129]
	v_exp_f32_e32 v116, v116
	v_exp_f32_e32 v117, v117
	v_exp_f32_e32 v122, v122
	v_exp_f32_e32 v123, v123
	v_exp_f32_e32 v118, v118
	v_exp_f32_e32 v119, v119
	v_exp_f32_e32 v120, v120
	v_exp_f32_e32 v121, v121
	v_pk_add_f32 v[124:125], v[212:213], 1.0 op_sel_hi:[1,0]
	v_pk_add_f32 v[128:129], v[228:229], 1.0 op_sel_hi:[1,0]
	v_pk_fma_f32 v[124:125], v[116:117], v[124:125], v[124:125]
	v_pk_fma_f32 v[122:123], v[122:123], v[126:127], v[126:127]
	v_pk_fma_f32 v[126:127], v[118:119], v[128:129], v[128:129]
	v_pk_fma_f32 v[128:129], v[120:121], v[114:115], v[114:115]
	v_mov_b64_e32 v[198:199], s[56:57]
	v_rcp_f32_e32 v244, v122
	v_add_u32_e32 v122, s42, v210
	v_rcp_f32_e32 v245, v123
	v_mad_i64_i32 v[122:123], s[26:27], v122, s61, v[198:199]
	v_lshl_add_u64 v[122:123], v[122:123], 0, s[40:41]
	v_lshl_add_u64 v[122:123], v[122:123], 0, s[6:7]
	v_rcp_f32_e32 v242, v124
	v_rcp_f32_e32 v243, v125
	v_rcp_f32_e32 v246, v126
	v_rcp_f32_e32 v247, v127
	v_rcp_f32_e32 v248, v128
	v_rcp_f32_e32 v249, v129
	v_lshl_add_u64 v[250:251], v[122:123], 0, v[186:187]
	v_or_b32_e32 v212, 16, v210
	v_ashrrev_i32_e32 v213, 31, v212
	v_add_u32_e32 v211, s42, v212
	s_waitcnt vmcnt(4)
; #define GAS __attribute__((address_space(1)))
; __device__ __forceinline__ v4u pack8(const float (&f)[8]) { v4u w; w.x = pk2(f[0], f[1]); w.y = pk2(f[2], f[3]); w.z = pk2(f[4], f[5]); w.w = pk2(f[6], f[7]); return w; }
; __device__ __forceinline__ float fexp2(float x) { return __builtin_amdgcn_exp2f(x); }
; __device__ __forceinline__ float frcp(float x) { return __builtin_amdgcn_rcpf(x); }
;     __device__ __forceinline__ void operator()(const af4 (&acc)[2][2][4][2], const pg8::Unit& u, int wr_, int wc_, int fr_, int fq_) const {
;     ...
;             for (int m = 0; m < 4; ++m) {
;                 if (ai == 0 && m == 0) load_raw(1);
;                 const int it = wr * 64 + m * 16 + fr;
;                 bf16x8 wf[4];
; #pragma unroll
;                 for (int ks = 0; ks < 4; ++ks) wf[ks] = *(const GAS bf16x8*)(wsg + (size_t)it * 128 + 32 * ks + 8 * fq);
;                 const float bsi = bs[grp * 128 + it];
;                 af4 vm[2] = {(af4){bsi, bsi, bsi, bsi}, (af4){bsi, bsi, bsi, bsi}};
; #pragma unroll
;                 for (int ks = 0; ks < 4; ++ks) {
; #pragma unroll
;                     for (int n = 0; n < 2; ++n) vm[n] = __builtin_amdgcn_mfma_f32_16x16x32_bf16(av[n][ks], wf[ks], vm[n], 0, 0, 0);
;                 }
;                 float o[8];
; #pragma unroll
;                 for (int n = 0; n < 2; ++n)
; #pragma unroll
;                     for (int e = 0; e < 4; e += 2) {
;                         const f32x2 uu = {acc[ai][0][m][n][e], acc[ai][0][m][n][e + 1]}, gg = {acc[ai][1][m][n][e], acc[ai][1][m][n][e + 1]}, vv = {vm[n][e], vm[n][e + 1]};
;                         const f32x2 ar = uu * (uu * uu * (-2.302208198f * 0.044715f) + (-2.302208198f));
;                         const f32x2 gs = gg * (-1.4426950408889634f);
;                         const f32x2 ea = {fexp2(ar.x), fexp2(ar.y)}, eb = {fexp2(gs.x), fexp2(gs.y)};
;                         const f32x2 q = eb + 1.0f, den = ea * q + q;
;                         const f32x2 r = {frcp(den.x), frcp(den.y)};
;                         const f32x2 w = (uu * gg) * vv * r;
;                         o[4 * n + e] = w.x; o[4 * n + e + 1] = w.y; }
;                 *(GAS v4u*)(Y + (size_t)(tok0 + it) * CW + chbase + 32 * wc + 8 * fq) = pack8(o);
;             }
	v_mov_b32_e32 v155, v154
	v_mov_b32_e32 v156, v154
	v_mov_b32_e32 v157, v154
	s_waitcnt vmcnt(3)
	s_nop 0
	v_mfma_f32_16x16x32_bf16 v[114:117], v[130:133], v[158:161], v[154:157]
	v_mfma_f32_16x16x32_bf16 v[118:121], v[134:137], v[158:161], v[154:157]
	s_waitcnt vmcnt(2)
	v_mfma_f32_16x16x32_bf16 v[114:117], v[142:145], v[170:173], v[114:117]
	v_mfma_f32_16x16x32_bf16 v[118:121], v[138:141], v[170:173], v[118:121]
	s_waitcnt vmcnt(1)
	v_mfma_f32_16x16x32_bf16 v[114:117], v[150:153], v[174:177], v[114:117]
	v_mfma_f32_16x16x32_bf16 v[226:229], v[146:149], v[174:177], v[118:121]
	global_load_dwordx4 v[174:177], v[216:217], off offset:256
	global_load_dwordx4 v[158:161], v[216:217], off offset:320
	global_load_dwordx4 v[170:173], v[220:221], off offset:256
	global_load_dwordx4 v[154:157], v[220:221], off offset:320
	s_waitcnt vmcnt(4)
	v_mfma_f32_16x16x32_bf16 v[230:233], v[166:169], v[222:225], v[114:117]
	global_load_dwordx4 v[126:129], v[216:217], off offset:384
	global_load_dwordx4 v[118:121], v[216:217], off offset:448
	global_load_dwordx4 v[122:125], v[220:221], off offset:384
	global_load_dwordx4 v[114:117], v[220:221], off offset:448
	v_mfma_f32_16x16x32_bf16 v[220:223], v[162:165], v[222:225], v[226:229]
	s_nop 2
	v_mul_f32_e64 v216, v234, v230
	v_mul_f32_e64 v217, v235, v231
	v_pk_mul_f32 v[224:225], v[236:237], v[232:233]
	v_pk_mul_f32 v[216:217], v[242:243], v[216:217]
	v_pk_mul_f32 v[224:225], v[244:245], v[224:225]
	v_pk_mul_f32 v[242:243], v[110:111], s[20:21] op_sel_hi:[1,0]
	v_pk_mul_f32 v[220:221], v[238:239], v[220:221]
	v_pk_mul_f32 v[222:223], v[240:241], v[222:223]
	v_pk_mul_f32 v[226:227], v[246:247], v[220:221]
	v_pk_mul_f32 v[228:229], v[248:249], v[222:223]
	v_cvt_pk_bf16_f32 v220, v216, v217
	v_cvt_pk_bf16_f32 v221, v224, v225
	v_cvt_pk_bf16_f32 v222, v226, v227
	v_lshlrev_b64 v[216:217], 8, v[212:213]
	v_cvt_pk_bf16_f32 v223, v228, v229
	global_store_dwordx4 v[250:251], v[220:223], off
	s_nop 0
	v_lshl_add_u64 v[216:217], v[218:219], 0, v[216:217]
	ds_read_b128 v[224:227], v189 offset:0
	ds_read_b128 v[228:231], v189 offset:1024
	ds_read_b128 v[232:235], v189 offset:2048
	ds_read_b128 v[236:239], v189 offset:3072
	v_pk_mul_f32 v[222:223], v[108:109], v[108:109]
	v_pk_mul_f32 v[240:241], v[106:107], v[106:107]
	v_pk_mul_f32 v[244:245], v[112:113], s[20:21] op_sel_hi:[1,0]
	v_pk_mul_f32 v[248:249], v[102:103], v[102:103]
	v_pk_mul_f32 v[250:251], v[98:99], s[20:21] op_sel_hi:[1,0]
	v_pk_mul_f32 v[98:99], v[100:101], s[20:21] op_sel_hi:[1,0]
	v_pk_fma_f32 v[100:101], v[240:241], s[16:17], v[196:197] op_sel_hi:[1,0,0] neg_lo:[1,0,0] neg_hi:[1,0,0]
	v_pk_fma_f32 v[222:223], v[222:223], s[16:17], v[196:197] op_sel_hi:[1,0,0] neg_lo:[1,0,0] neg_hi:[1,0,0]
	v_exp_f32_e32 v240, v242
	v_exp_f32_e32 v241, v243
	v_exp_f32_e32 v242, v244
	v_exp_f32_e32 v243, v245
	v_pk_fma_f32 v[244:245], v[248:249], s[16:17], v[196:197] op_sel_hi:[1,0,0] neg_lo:[1,0,0] neg_hi:[1,0,0]
	v_exp_f32_e32 v248, v250
	v_exp_f32_e32 v249, v251
	v_exp_f32_e32 v250, v98
	v_exp_f32_e32 v251, v99
	v_pk_mul_f32 v[98:99], v[106:107], v[100:101]
	v_pk_mul_f32 v[100:101], v[108:109], v[222:223]
	v_pk_mul_f32 v[110:111], v[106:107], v[110:111]
	v_pk_mul_f32 v[112:113], v[108:109], v[112:113]
	v_pk_mul_f32 v[246:247], v[104:105], v[104:105]
	v_exp_f32_e32 v106, v98
	v_exp_f32_e32 v107, v99
	v_exp_f32_e32 v108, v100
	v_exp_f32_e32 v109, v101
	v_pk_fma_f32 v[246:247], v[246:247], s[16:17], v[196:197] op_sel_hi:[1,0,0] neg_lo:[1,0,0] neg_hi:[1,0,0]
	v_pk_mul_f32 v[102:103], v[102:103], v[244:245]
	v_pk_mul_f32 v[104:105], v[104:105], v[246:247]
	v_exp_f32_e32 v244, v102
	v_exp_f32_e32 v245, v103
	v_exp_f32_e32 v246, v104
	v_exp_f32_e32 v247, v105
	v_pk_add_f32 v[102:103], v[240:241], 1.0 op_sel_hi:[1,0]
	v_pk_add_f32 v[104:105], v[242:243], 1.0 op_sel_hi:[1,0]
	v_pk_fma_f32 v[106:107], v[106:107], v[102:103], v[102:103]
	v_pk_fma_f32 v[108:109], v[108:109], v[104:105], v[104:105]
	v_pk_add_f32 v[240:241], v[248:249], 1.0 op_sel_hi:[1,0]
	v_pk_add_f32 v[242:243], v[250:251], 1.0 op_sel_hi:[1,0]
	v_mov_b32_e32 v220, v179
	v_mov_b32_e32 v221, v220
	v_mov_b32_e32 v222, v220
	v_mov_b32_e32 v223, v220
	s_waitcnt lgkmcnt(3)
	s_nop 0
	v_mfma_f32_16x16x32_bf16 v[98:101], v[130:133], v[224:227], v[220:223]
	v_mfma_f32_16x16x32_bf16 v[102:105], v[134:137], v[224:227], v[220:223]
	v_rcp_f32_e32 v224, v106
	v_rcp_f32_e32 v225, v107
	v_rcp_f32_e32 v226, v108
	s_waitcnt lgkmcnt(2)
	v_mfma_f32_16x16x32_bf16 v[98:101], v[142:145], v[228:231], v[98:101]
	v_rcp_f32_e32 v227, v109
	v_pk_fma_f32 v[220:221], v[244:245], v[240:241], v[240:241]
	v_pk_fma_f32 v[222:223], v[246:247], v[242:243], v[242:243]
	v_mfma_f32_16x16x32_bf16 v[102:105], v[138:141], v[228:231], v[102:105]
	v_rcp_f32_e32 v220, v220
	v_rcp_f32_e32 v221, v221
	v_rcp_f32_e32 v222, v222
	s_waitcnt lgkmcnt(1)
	v_mfma_f32_16x16x32_bf16 v[106:109], v[150:153], v[232:235], v[98:101]
	v_rcp_f32_e32 v223, v223
	v_mad_i64_i32 v[228:229], s[26:27], v211, s61, v[198:199]
	v_mfma_f32_16x16x32_bf16 v[100:103], v[146:149], v[232:235], v[102:105]
	v_or_b32_e32 v98, 32, v210
	v_ashrrev_i32_e32 v99, 31, v98
	v_pk_mul_f32 v[234:235], v[86:87], v[86:87]
	s_waitcnt lgkmcnt(0)
; #define GAS __attribute__((address_space(1)))
; __device__ __forceinline__ v4u pack8(const float (&f)[8]) { v4u w; w.x = pk2(f[0], f[1]); w.y = pk2(f[2], f[3]); w.z = pk2(f[4], f[5]); w.w = pk2(f[6], f[7]); return w; }
; __device__ __forceinline__ float fexp2(float x) { return __builtin_amdgcn_exp2f(x); }
; __device__ __forceinline__ float frcp(float x) { return __builtin_amdgcn_rcpf(x); }
;     __device__ __forceinline__ void operator()(const af4 (&acc)[2][2][4][2], const pg8::Unit& u, int wr_, int wc_, int fr_, int fq_) const {
;     ...
;             for (int m = 0; m < 4; ++m) {
;                 if (ai == 0 && m == 0) load_raw(1);
;                 const int it = wr * 64 + m * 16 + fr;
;                 bf16x8 wf[4];
; #pragma unroll
;                 for (int ks = 0; ks < 4; ++ks) wf[ks] = *(const GAS bf16x8*)(wsg + (size_t)it * 128 + 32 * ks + 8 * fq);
;                 const float bsi = bs[grp * 128 + it];
;                 af4 vm[2] = {(af4){bsi, bsi, bsi, bsi}, (af4){bsi, bsi, bsi, bsi}};
; #pragma unroll
;                 for (int ks = 0; ks < 4; ++ks) {
; #pragma unroll
;                     for (int n = 0; n < 2; ++n) vm[n] = __builtin_amdgcn_mfma_f32_16x16x32_bf16(av[n][ks], wf[ks], vm[n], 0, 0, 0);
;                 }
;                 float o[8];
; #pragma unroll
;                 for (int n = 0; n < 2; ++n)
; #pragma unroll
;                     for (int e = 0; e < 4; e += 2) {
;                         const f32x2 uu = {acc[ai][0][m][n][e], acc[ai][0][m][n][e + 1]}, gg = {acc[ai][1][m][n][e], acc[ai][1][m][n][e + 1]}, vv = {vm[n][e], vm[n][e + 1]};
;                         const f32x2 ar = uu * (uu * uu * (-2.302208198f * 0.044715f) + (-2.302208198f));
;                         const f32x2 gs = gg * (-1.4426950408889634f);
;                         const f32x2 ea = {fexp2(ar.x), fexp2(ar.y)}, eb = {fexp2(gs.x), fexp2(gs.y)};
;                         const f32x2 q = eb + 1.0f, den = ea * q + q;
;                         const f32x2 r = {frcp(den.x), frcp(den.y)};
;                         const f32x2 w = (uu * gg) * vv * r;
;                         o[4 * n + e] = w.x; o[4 * n + e + 1] = w.y; }
;                 *(GAS v4u*)(Y + (size_t)(tok0 + it) * CW + chbase + 32 * wc + 8 * fq) = pack8(o);
;             }
	v_mfma_f32_16x16x32_bf16 v[104:107], v[166:169], v[236:239], v[106:109]
	v_mul_f32_e64 v240, v88, v84
	v_mul_f32_e64 v241, v89, v85
	v_pk_mul_f32 v[232:233], v[88:89], v[88:89]
	v_mfma_f32_16x16x32_bf16 v[100:103], v[162:165], v[236:239], v[100:103]
	v_lshl_add_u64 v[108:109], v[228:229], 0, s[40:41]
	v_lshl_add_u64 v[108:109], v[108:109], 0, s[6:7]
	v_lshl_add_u64 v[108:109], v[108:109], 0, v[186:187]
	s_nop 0
	v_pk_mul_f32 v[104:105], v[110:111], v[104:105]
	v_pk_mul_f32 v[106:107], v[112:113], v[106:107]
	s_nop 1
	v_pk_mul_f32 v[100:101], v[252:253], v[100:101]
	v_pk_mul_f32 v[102:103], v[192:193], v[102:103]
	v_pk_mul_f32 v[104:105], v[224:225], v[104:105]
	v_pk_mul_f32 v[106:107], v[226:227], v[106:107]
	v_pk_mul_f32 v[110:111], v[220:221], v[100:101]
	v_pk_mul_f32 v[112:113], v[222:223], v[102:103]
	v_cvt_pk_bf16_f32 v100, v104, v105
	v_cvt_pk_bf16_f32 v101, v106, v107
	v_cvt_pk_bf16_f32 v102, v110, v111
	v_pk_mul_f32 v[106:107], v[90:91], v[90:91]
	v_cvt_pk_bf16_f32 v103, v112, v113
	global_store_dwordx4 v[108:109], v[100:103], off
	s_nop 0
	v_pk_mul_f32 v[112:113], v[94:95], s[20:21] op_sel_hi:[1,0]
	v_lshlrev_b64 v[100:101], 8, v[98:99]
	v_lshl_add_u64 v[102:103], v[218:219], 0, v[100:101]
	ds_read_b128 v[108:111], v189 offset:4096
	ds_read_b128 v[220:223], v189 offset:5120
	ds_read_b128 v[224:227], v189 offset:6144
	ds_read_b128 v[228:231], v189 offset:7168
	v_pk_mul_f32 v[100:101], v[92:93], v[92:93]
	v_pk_mul_f32 v[192:193], v[96:97], s[20:21] op_sel_hi:[1,0]
	v_pk_mul_f32 v[236:237], v[82:83], s[20:21] op_sel_hi:[1,0]
	v_pk_mul_f32 v[238:239], v[86:87], v[82:83]
	v_pk_mul_f32 v[82:83], v[84:85], s[20:21] op_sel_hi:[1,0]
	v_pk_fma_f32 v[84:85], v[106:107], s[16:17], v[196:197] op_sel_hi:[1,0,0] neg_lo:[1,0,0] neg_hi:[1,0,0]
	v_exp_f32_e32 v106, v112
	v_exp_f32_e32 v107, v113
	v_pk_fma_f32 v[100:101], v[100:101], s[16:17], v[196:197] op_sel_hi:[1,0,0] neg_lo:[1,0,0] neg_hi:[1,0,0]
	v_exp_f32_e32 v112, v192
	v_exp_f32_e32 v113, v193
	v_pk_fma_f32 v[192:193], v[234:235], s[16:17], v[196:197] op_sel_hi:[1,0,0] neg_lo:[1,0,0] neg_hi:[1,0,0]
	v_exp_f32_e32 v234, v236
	v_exp_f32_e32 v235, v237
	v_exp_f32_e32 v236, v82
	v_exp_f32_e32 v237, v83
	v_pk_mul_f32 v[82:83], v[90:91], v[84:85]
	v_pk_mul_f32 v[84:85], v[92:93], v[100:101]
	v_pk_mul_f32 v[94:95], v[90:91], v[94:95]
	v_pk_mul_f32 v[96:97], v[92:93], v[96:97]
	v_exp_f32_e32 v90, v82
	v_exp_f32_e32 v91, v83
	v_exp_f32_e32 v92, v84
	v_exp_f32_e32 v93, v85
	v_pk_fma_f32 v[232:233], v[232:233], s[16:17], v[196:197] op_sel_hi:[1,0,0] neg_lo:[1,0,0] neg_hi:[1,0,0]
	v_pk_mul_f32 v[86:87], v[86:87], v[192:193]
	v_pk_mul_f32 v[88:89], v[88:89], v[232:233]
	v_exp_f32_e32 v100, v86
	v_exp_f32_e32 v101, v87
	v_pk_add_f32 v[86:87], v[106:107], 1.0 op_sel_hi:[1,0]
	v_exp_f32_e32 v192, v88
	v_exp_f32_e32 v193, v89
	v_pk_add_f32 v[88:89], v[112:113], 1.0 op_sel_hi:[1,0]
	v_pk_fma_f32 v[90:91], v[90:91], v[86:87], v[86:87]
	v_pk_fma_f32 v[92:93], v[92:93], v[88:89], v[88:89]
	v_pk_add_f32 v[112:113], v[234:235], 1.0 op_sel_hi:[1,0]
	v_pk_add_f32 v[232:233], v[236:237], 1.0 op_sel_hi:[1,0]
	v_pk_fma_f32 v[100:101], v[100:101], v[112:113], v[112:113]
	v_rcp_f32_e32 v90, v90
	v_rcp_f32_e32 v91, v91
	v_rcp_f32_e32 v92, v92
	v_rcp_f32_e32 v93, v93
	v_add_u32_e32 v99, s42, v98
	v_pk_mul_f32 v[112:113], v[78:79], s[20:21] op_sel_hi:[1,0]
	v_pk_mul_f32 v[78:79], v[74:75], v[78:79]
	v_mov_b32_e32 v104, v181
	v_mov_b32_e32 v105, v104
	v_mov_b32_e32 v106, v104
	v_mov_b32_e32 v107, v104
	s_waitcnt lgkmcnt(3)
	s_nop 0
	v_mfma_f32_16x16x32_bf16 v[82:85], v[130:133], v[108:111], v[104:107]
	v_mfma_f32_16x16x32_bf16 v[86:89], v[134:137], v[108:111], v[104:107]
	v_mad_i64_i32 v[108:109], s[26:27], v99, s61, v[198:199]
	v_lshl_add_u64 v[108:109], v[108:109], 0, s[40:41]
	s_waitcnt lgkmcnt(2)
	v_mfma_f32_16x16x32_bf16 v[82:85], v[142:145], v[220:223], v[82:85]
	v_fma_f32 v104, v192, v232, v232
	v_fma_f32 v105, v193, v233, v233
	v_rcp_f32_e32 v106, v100
	v_rcp_f32_e32 v107, v101
	v_mfma_f32_16x16x32_bf16 v[86:89], v[138:141], v[220:223], v[86:89]
	v_rcp_f32_e32 v104, v104
	v_rcp_f32_e32 v105, v105
	v_lshl_add_u64 v[108:109], v[108:109], 0, s[6:7]
	s_waitcnt lgkmcnt(1)
	v_mfma_f32_16x16x32_bf16 v[82:85], v[150:153], v[224:227], v[82:85]
	v_lshl_add_u64 v[108:109], v[108:109], 0, v[186:187]
	v_or_b32_e32 v100, 48, v210
	v_ashrrev_i32_e32 v101, 31, v100
	v_mfma_f32_16x16x32_bf16 v[86:89], v[146:149], v[224:227], v[86:89]
	v_mul_f32_e64 v110, v74, v74
	v_mul_f32_e64 v111, v75, v75
	v_pk_mul_f32 v[192:193], v[80:81], s[20:21] op_sel_hi:[1,0]
	v_pk_mul_f32 v[220:221], v[70:71], v[70:71]
	s_waitcnt lgkmcnt(0)
; #define GAS __attribute__((address_space(1)))
;     __device__ __forceinline__ void operator()(const af4 (&acc)[2][2][4][2], const pg8::Unit& u, int wr_, int wc_, int fr_, int fq_) const {
;     ...
;             for (int ks = 0; ks < 4; ++ks) {
;                 const int j0 = tok0 + 32 * ks + 8 * fq;
;                 f32x4 st[4];
; #pragma unroll
;                 for (int q = 0; q < 4; ++q) st[q] = *(const GAS f32x4*)(stats + (size_t)(j0 + 2 * q) * 2);
; #pragma unroll
;                 for (int n = 0; n < 2; ++n) {
;                     float vf[8];
;                     unpack8(raw[n][ks], vf);
; #pragma unroll
;     ...
;             for (int m = 0; m < 4; ++m) {
;                 if (ai == 0 && m == 0) load_raw(1);
;                 const int it = wr * 64 + m * 16 + fr;
;                 bf16x8 wf[4];
; #pragma unroll
;                 for (int ks = 0; ks < 4; ++ks) wf[ks] = *(const GAS bf16x8*)(wsg + (size_t)it * 128 + 32 * ks + 8 * fq);
;                 const float bsi = bs[grp * 128 + it];
;                 af4 vm[2] = {(af4){bsi, bsi, bsi, bsi}, (af4){bsi, bsi, bsi, bsi}};
; #pragma unroll
;                 for (int ks = 0; ks < 4; ++ks) {
; #pragma unroll
;                     for (int n = 0; n < 2; ++n) vm[n] = __builtin_amdgcn_mfma_f32_16x16x32_bf16(av[n][ks], wf[ks], vm[n], 0, 0, 0);
;                 }
;                 float o[8];
; #pragma unroll
;                 for (int n = 0; n < 2; ++n)
; #pragma unroll
;                     for (int e = 0; e < 4; e += 2) {
;                         const f32x2 uu = {acc[ai][0][m][n][e], acc[ai][0][m][n][e + 1]}, gg = {acc[ai][1][m][n][e], acc[ai][1][m][n][e + 1]}, vv = {vm[n][e], vm[n][e + 1]};
;                         const f32x2 ar = uu * (uu * uu * (-2.302208198f * 0.044715f) + (-2.302208198f));
;                         const f32x2 gs = gg * (-1.4426950408889634f);
;                         const f32x2 ea = {fexp2(ar.x), fexp2(ar.y)}, eb = {fexp2(gs.x), fexp2(gs.y)};
;                         const f32x2 q = eb + 1.0f, den = ea * q + q;
;                         const f32x2 r = {frcp(den.x), frcp(den.y)};
;                         const f32x2 w = (uu * gg) * vv * r;
;                         o[4 * n + e] = w.x; o[4 * n + e + 1] = w.y; }
;                 *(GAS v4u*)(Y + (size_t)(tok0 + it) * CW + chbase + 32 * wc + 8 * fq) = pack8(o);
;             }
	v_mfma_f32_16x16x32_bf16 v[82:85], v[166:169], v[228:231], v[82:85]
	v_mul_f32_e64 v222, v66, s20
	v_mul_f32_e64 v223, v67, s20
	v_pk_mul_f32 v[224:225], v[70:71], v[66:67]
	v_pk_mul_f32 v[66:67], v[68:69], s[20:21] op_sel_hi:[1,0]
	v_mfma_f32_16x16x32_bf16 v[86:89], v[162:165], v[228:231], v[86:89]
	v_mul_f32_e64 v226, v72, v68
	v_mul_f32_e64 v227, v73, v69
	s_nop 0
	v_pk_mul_f32 v[82:83], v[94:95], v[82:83]
	v_pk_mul_f32 v[84:85], v[96:97], v[84:85]
	v_pk_mul_f32 v[82:83], v[90:91], v[82:83]
	v_pk_mul_f32 v[84:85], v[92:93], v[84:85]
	s_nop 0
	v_pk_mul_f32 v[86:87], v[238:239], v[86:87]
	v_pk_mul_f32 v[88:89], v[240:241], v[88:89]
	v_pk_mul_f32 v[86:87], v[106:107], v[86:87]
	v_pk_mul_f32 v[88:89], v[104:105], v[88:89]
	v_cvt_pk_bf16_f32 v82, v82, v83
	v_cvt_pk_bf16_f32 v83, v84, v85
	v_cvt_pk_bf16_f32 v84, v86, v87
	v_pk_fma_f32 v[68:69], v[110:111], s[16:17], v[196:197] op_sel_hi:[1,0,0] neg_lo:[1,0,0] neg_hi:[1,0,0]
	v_cvt_pk_bf16_f32 v85, v88, v89
	global_store_dwordx4 v[108:109], v[82:85], off
	s_nop 0
	v_exp_f32_e32 v110, v112
	v_lshlrev_b64 v[84:85], 8, v[100:101]
	v_lshl_add_u64 v[104:105], v[218:219], 0, v[84:85]
	ds_read_b128 v[86:89], v189 offset:8192
	ds_read_b128 v[90:93], v189 offset:9216
	ds_read_b128 v[94:97], v189 offset:10240
	ds_read_b128 v[106:109], v189 offset:11264
	v_pk_mul_f32 v[84:85], v[76:77], v[76:77]
	v_pk_mul_f32 v[218:219], v[72:73], v[72:73]
	v_exp_f32_e32 v111, v113
	v_pk_fma_f32 v[84:85], v[84:85], s[16:17], v[196:197] op_sel_hi:[1,0,0] neg_lo:[1,0,0] neg_hi:[1,0,0]
	v_exp_f32_e32 v112, v192
	v_exp_f32_e32 v113, v193
	v_pk_fma_f32 v[192:193], v[220:221], s[16:17], v[196:197] op_sel_hi:[1,0,0] neg_lo:[1,0,0] neg_hi:[1,0,0]
	v_pk_fma_f32 v[218:219], v[218:219], s[16:17], v[196:197] op_sel_hi:[1,0,0] neg_lo:[1,0,0] neg_hi:[1,0,0]
	v_pk_mul_f32 v[68:69], v[74:75], v[68:69]
	v_exp_f32_e32 v220, v222
	v_exp_f32_e32 v221, v223
	v_exp_f32_e32 v66, v66
	v_exp_f32_e32 v67, v67
	v_pk_mul_f32 v[74:75], v[76:77], v[84:85]
	v_pk_mul_f32 v[70:71], v[70:71], v[192:193]
	v_pk_mul_f32 v[72:73], v[72:73], v[218:219]
	v_exp_f32_e32 v68, v68
	v_exp_f32_e32 v69, v69
	v_exp_f32_e32 v74, v74
	v_exp_f32_e32 v75, v75
	v_exp_f32_e32 v70, v70
	v_exp_f32_e32 v71, v71
	v_exp_f32_e32 v72, v72
	v_exp_f32_e32 v73, v73
	v_pk_mul_f32 v[80:81], v[76:77], v[80:81]
	v_pk_add_f32 v[76:77], v[110:111], 1.0 op_sel_hi:[1,0]
	v_pk_add_f32 v[110:111], v[112:113], 1.0 op_sel_hi:[1,0]
	v_pk_add_f32 v[112:113], v[220:221], 1.0 op_sel_hi:[1,0]
	v_pk_add_f32 v[192:193], v[66:67], 1.0 op_sel_hi:[1,0]
	v_pk_fma_f32 v[76:77], v[68:69], v[76:77], v[76:77]
	v_pk_fma_f32 v[74:75], v[74:75], v[110:111], v[110:111]
	v_pk_fma_f32 v[110:111], v[70:71], v[112:113], v[112:113]
	v_pk_fma_f32 v[112:113], v[72:73], v[192:193], v[192:193]
	v_rcp_f32_e32 v76, v76
	v_rcp_f32_e32 v77, v77
	v_rcp_f32_e32 v74, v74
	v_rcp_f32_e32 v75, v75
	v_add_u32_e32 v99, s23, v210
	s_waitcnt vmcnt(3)
	v_mov_b32_e32 v82, v183
	v_mov_b32_e32 v83, v82
	v_mov_b32_e32 v84, v82
	v_mov_b32_e32 v85, v82
	s_waitcnt lgkmcnt(3)
	s_nop 0
	v_mfma_f32_16x16x32_bf16 v[66:69], v[130:133], v[86:89], v[82:85]
	v_lshlrev_b32_e32 v130, 16, v156
	v_and_b32_e32 v131, 0xffff0000, v156
	v_lshlrev_b32_e32 v132, 16, v157
	v_mfma_f32_16x16x32_bf16 v[70:73], v[134:137], v[86:89], v[82:85]
	v_rcp_f32_e32 v86, v112
	v_rcp_f32_e32 v87, v113
	v_lshlrev_b32_e32 v112, 16, v155
	s_waitcnt lgkmcnt(2)
	v_mfma_f32_16x16x32_bf16 v[66:69], v[142:145], v[90:93], v[66:69]
	v_rcp_f32_e32 v84, v110
	v_rcp_f32_e32 v85, v111
	v_or_b32_e32 v82, s23, v209
	v_mfma_f32_16x16x32_bf16 v[70:73], v[138:141], v[90:93], v[70:73]
	v_add_u32_e32 v90, s42, v100
	v_mad_i64_i32 v[90:91], s[26:27], v90, s61, v[198:199]
	s_waitcnt lgkmcnt(1)
	v_mfma_f32_16x16x32_bf16 v[66:69], v[150:153], v[94:97], v[66:69]
	v_lshl_add_u64 v[90:91], v[90:91], 0, s[40:41]
	v_lshl_add_u64 v[90:91], v[90:91], 0, s[6:7]
	v_ashrrev_i32_e32 v83, 31, v82
	v_mfma_f32_16x16x32_bf16 v[70:73], v[146:149], v[94:97], v[70:73]
	v_lshl_add_u64 v[90:91], v[90:91], 0, v[186:187]
	v_lshl_add_u32 v88, v82, 3, s98
	v_lshlrev_b32_e32 v92, 16, v177
	s_waitcnt lgkmcnt(0)
	v_mfma_f32_16x16x32_bf16 v[66:69], v[166:169], v[106:109], v[66:69]
	v_and_b32_e32 v93, 0xffff0000, v177
	v_lshlrev_b32_e32 v94, 16, v170
	v_and_b32_e32 v95, 0xffff0000, v170
	v_mfma_f32_16x16x32_bf16 v[70:73], v[162:165], v[106:109], v[70:73]
	v_lshlrev_b32_e32 v96, 16, v171
	s_nop 2
	v_pk_mul_f32 v[66:67], v[78:79], v[66:67]
	v_pk_mul_f32 v[68:69], v[80:81], v[68:69]
	v_pk_mul_f32 v[66:67], v[76:77], v[66:67]
	v_pk_mul_f32 v[68:69], v[74:75], v[68:69]
	v_pk_mul_f32 v[70:71], v[224:225], v[70:71]
	v_pk_mul_f32 v[72:73], v[226:227], v[72:73]
	v_pk_mul_f32 v[70:71], v[84:85], v[70:71]
	v_pk_mul_f32 v[72:73], v[86:87], v[72:73]
	v_cvt_pk_bf16_f32 v66, v66, v67
	v_cvt_pk_bf16_f32 v67, v68, v69
	v_cvt_pk_bf16_f32 v68, v70, v71
	v_or_b32_e32 v84, 32, v82
	v_cvt_pk_bf16_f32 v69, v72, v73
	global_store_dwordx4 v[90:91], v[66:69], off
	ds_read_b128 v[66:69], v88
	s_nop 0
	ds_read_b128 v[70:73], v88 offset:16
	ds_read_b128 v[74:77], v88 offset:32
	ds_read_b128 v[78:81], v88 offset:48
	v_ashrrev_i32_e32 v85, 31, v84
	v_lshl_add_u32 v88, v84, 3, s98
	v_lshlrev_b32_e32 v84, 16, v174
	v_and_b32_e32 v85, 0xffff0000, v174
	v_lshlrev_b32_e32 v86, 16, v175
	v_and_b32_e32 v87, 0xffff0000, v175
	v_lshlrev_b32_e32 v90, 16, v176
	v_and_b32_e32 v91, 0xffff0000, v176
	v_and_b32_e32 v97, 0xffff0000, v171
	v_lshlrev_b32_e32 v106, 16, v172
	v_and_b32_e32 v107, 0xffff0000, v172
	v_lshlrev_b32_e32 v108, 16, v173
	v_and_b32_e32 v109, 0xffff0000, v173
	v_lshlrev_b32_e32 v110, 16, v154
	v_and_b32_e32 v111, 0xffff0000, v154
	v_and_b32_e32 v113, 0xffff0000, v155
	v_and_b32_e32 v133, 0xffff0000, v157
	v_pk_mul_f32 v[134:135], v[54:55], v[54:55]
	v_pk_mul_f32 v[136:137], v[50:51], s[20:21] op_sel_hi:[1,0]
	v_pk_mul_f32 v[138:139], v[54:55], v[50:51]
	v_pk_mul_f32 v[50:51], v[52:53], s[20:21] op_sel_hi:[1,0]
	v_pk_mul_f32 v[140:141], v[56:57], v[52:53]
	s_waitcnt lgkmcnt(3)
; #define GAS __attribute__((address_space(1)))
; __device__ __forceinline__ void unpack8(const v4u w, float (&f)[8]) { f[0] = bflo(w.x); f[1] = bfhi(w.x); f[2] = bflo(w.y); f[3] = bfhi(w.y); f[4] = bflo(w.z); f[5] = bfhi(w.z); f[6] = bflo(w.w); f[7] = bfhi(w.w); }
; __device__ __forceinline__ v4u pack8(const float (&f)[8]) { v4u w; w.x = pk2(f[0], f[1]); w.y = pk2(f[2], f[3]); w.z = pk2(f[4], f[5]); w.w = pk2(f[6], f[7]); return w; }
;     __device__ __forceinline__ void operator()(const af4 (&acc)[2][2][4][2], const pg8::Unit& u, int wr_, int wc_, int fr_, int fq_) const {
;     ...
;             for (int ks = 0; ks < 4; ++ks) {
;                 const int j0 = tok0 + 32 * ks + 8 * fq;
;                 f32x4 st[4];
; #pragma unroll
;                 for (int q = 0; q < 4; ++q) st[q] = *(const GAS f32x4*)(stats + (size_t)(j0 + 2 * q) * 2);
; #pragma unroll
;                 for (int n = 0; n < 2; ++n) {
;                     float vf[8];
;                     unpack8(raw[n][ks], vf);
; #pragma unroll
;                     for (int q = 0; q < 4; ++q) { f32x2 t = {vf[2 * q], vf[2 * q + 1]}; t = t * (f32x2){st[q].z, st[q].w} + (f32x2){st[q].x, st[q].y}; t = t * lg[n] + lb[n]; vf[2 * q] = t.x; vf[2 * q + 1] = t.y; }
;                     av[n][ks] = __builtin_bit_cast(bf16x8, pack8(vf));
;                 }
;             }
	v_pk_fma_f32 v[84:85], v[68:69], v[84:85], v[66:67]
	s_waitcnt lgkmcnt(2)
	v_pk_fma_f32 v[86:87], v[72:73], v[86:87], v[70:71]
	s_waitcnt lgkmcnt(1)
	v_pk_fma_f32 v[90:91], v[76:77], v[90:91], v[74:75]
	s_waitcnt lgkmcnt(0)
	v_pk_fma_f32 v[92:93], v[80:81], v[92:93], v[78:79]
	v_pk_fma_f32 v[66:67], v[68:69], v[94:95], v[66:67]
	v_pk_fma_f32 v[68:69], v[72:73], v[96:97], v[70:71]
	v_pk_fma_f32 v[70:71], v[76:77], v[106:107], v[74:75]
	v_pk_fma_f32 v[72:73], v[80:81], v[108:109], v[78:79]
	v_pk_fma_f32 v[74:75], v[208:209], v[84:85], v[206:207] op_sel_hi:[0,1,0]
	v_pk_fma_f32 v[76:77], v[208:209], v[86:87], v[206:207] op_sel_hi:[0,1,0]
	v_pk_fma_f32 v[78:79], v[208:209], v[90:91], v[206:207] op_sel_hi:[0,1,0]
	v_pk_fma_f32 v[80:81], v[208:209], v[92:93], v[206:207] op_sel_hi:[0,1,0]
	v_pk_fma_f32 v[66:67], v[202:203], v[66:67], v[204:205] op_sel_hi:[0,1,0]
	v_pk_fma_f32 v[68:69], v[202:203], v[68:69], v[204:205] op_sel_hi:[0,1,0]
	v_pk_fma_f32 v[84:85], v[202:203], v[70:71], v[204:205] op_sel_hi:[0,1,0]
	v_pk_fma_f32 v[86:87], v[202:203], v[72:73], v[204:205] op_sel_hi:[0,1,0]
	v_cvt_pk_bf16_f32 v70, v74, v75
	v_cvt_pk_bf16_f32 v71, v76, v77
	v_cvt_pk_bf16_f32 v72, v78, v79
	v_cvt_pk_bf16_f32 v73, v80, v81
	v_cvt_pk_bf16_f32 v66, v66, v67
	v_cvt_pk_bf16_f32 v67, v68, v69
	v_cvt_pk_bf16_f32 v68, v84, v85
	v_cvt_pk_bf16_f32 v69, v86, v87
	ds_read_b128 v[74:77], v88
	ds_read_b128 v[78:81], v88 offset:16
	ds_read_b128 v[84:87], v88 offset:32
	s_nop 0
	ds_read_b128 v[88:91], v88 offset:48
	v_or_b32_e32 v92, 64, v82
	v_ashrrev_i32_e32 v93, 31, v92
	v_lshl_add_u32 v96, v92, 3, s98
	v_lshlrev_b32_e32 v92, 16, v158
	v_and_b32_e32 v93, 0xffff0000, v158
	v_lshlrev_b32_e32 v94, 16, v159
	v_and_b32_e32 v95, 0xffff0000, v159
	v_lshlrev_b32_e32 v106, 16, v160
	v_and_b32_e32 v107, 0xffff0000, v160
	v_lshlrev_b32_e32 v108, 16, v161
	v_and_b32_e32 v109, 0xffff0000, v161
	v_or_b32_e32 v82, 0x60, v82
	v_ashrrev_i32_e32 v83, 31, v82
	s_waitcnt lgkmcnt(3)
	v_pk_fma_f32 v[92:93], v[76:77], v[92:93], v[74:75]
	s_waitcnt lgkmcnt(2)
	v_pk_fma_f32 v[94:95], v[80:81], v[94:95], v[78:79]
	s_waitcnt lgkmcnt(1)
	v_pk_fma_f32 v[106:107], v[86:87], v[106:107], v[84:85]
	s_waitcnt lgkmcnt(0)
	v_pk_fma_f32 v[108:109], v[90:91], v[108:109], v[88:89]
	v_pk_fma_f32 v[74:75], v[76:77], v[110:111], v[74:75]
	v_pk_fma_f32 v[76:77], v[80:81], v[112:113], v[78:79]
	v_pk_fma_f32 v[78:79], v[86:87], v[130:131], v[84:85]
	v_pk_fma_f32 v[80:81], v[90:91], v[132:133], v[88:89]
	v_pk_fma_f32 v[84:85], v[208:209], v[92:93], v[206:207] op_sel_hi:[0,1,0]
	v_pk_fma_f32 v[86:87], v[208:209], v[94:95], v[206:207] op_sel_hi:[0,1,0]
	v_pk_fma_f32 v[88:89], v[208:209], v[106:107], v[206:207] op_sel_hi:[0,1,0]
	v_pk_fma_f32 v[90:91], v[208:209], v[108:109], v[206:207] op_sel_hi:[0,1,0]
	v_pk_fma_f32 v[74:75], v[202:203], v[74:75], v[204:205] op_sel_hi:[0,1,0]
	v_pk_fma_f32 v[76:77], v[202:203], v[76:77], v[204:205] op_sel_hi:[0,1,0]
	v_pk_fma_f32 v[92:93], v[202:203], v[78:79], v[204:205] op_sel_hi:[0,1,0]
	v_pk_fma_f32 v[94:95], v[202:203], v[80:81], v[204:205] op_sel_hi:[0,1,0]
	v_cvt_pk_bf16_f32 v78, v84, v85
	v_cvt_pk_bf16_f32 v79, v86, v87
	v_cvt_pk_bf16_f32 v80, v88, v89
	v_cvt_pk_bf16_f32 v81, v90, v91
	v_cvt_pk_bf16_f32 v74, v74, v75
	v_cvt_pk_bf16_f32 v75, v76, v77
	v_cvt_pk_bf16_f32 v76, v92, v93
	v_cvt_pk_bf16_f32 v77, v94, v95
	ds_read_b128 v[84:87], v96
	ds_read_b128 v[88:91], v96 offset:16
	ds_read_b128 v[92:95], v96 offset:32
	ds_read_b128 v[106:109], v96 offset:48
	v_lshl_add_u32 v110, v82, 3, s98
	v_lshlrev_b32_e32 v82, 16, v126
	v_and_b32_e32 v83, 0xffff0000, v126
	v_lshlrev_b32_e32 v96, 16, v127
	v_and_b32_e32 v97, 0xffff0000, v127
	v_lshlrev_b32_e32 v112, 16, v128
	v_and_b32_e32 v113, 0xffff0000, v128
	v_lshlrev_b32_e32 v126, 16, v129
	v_and_b32_e32 v127, 0xffff0000, v129
	v_lshlrev_b32_e32 v128, 16, v122
	v_and_b32_e32 v129, 0xffff0000, v122
	v_lshlrev_b32_e32 v122, 16, v123
	v_and_b32_e32 v123, 0xffff0000, v123
	v_lshlrev_b32_e32 v130, 16, v124
	v_and_b32_e32 v131, 0xffff0000, v124
	v_lshlrev_b32_e32 v124, 16, v125
	v_and_b32_e32 v125, 0xffff0000, v125
	v_pk_mul_f32 v[132:133], v[56:57], v[56:57]
	s_waitcnt lgkmcnt(3)
	v_pk_fma_f32 v[82:83], v[86:87], v[82:83], v[84:85]
	s_waitcnt lgkmcnt(2)
	v_pk_fma_f32 v[96:97], v[90:91], v[96:97], v[88:89]
	s_waitcnt lgkmcnt(1)
	v_pk_fma_f32 v[112:113], v[94:95], v[112:113], v[92:93]
	s_waitcnt lgkmcnt(0)
	v_pk_fma_f32 v[126:127], v[108:109], v[126:127], v[106:107]
	v_pk_fma_f32 v[84:85], v[86:87], v[128:129], v[84:85]
	v_pk_fma_f32 v[86:87], v[90:91], v[122:123], v[88:89]
	v_pk_fma_f32 v[88:89], v[94:95], v[130:131], v[92:93]
	v_pk_fma_f32 v[90:91], v[108:109], v[124:125], v[106:107]
	v_pk_fma_f32 v[82:83], v[208:209], v[82:83], v[206:207] op_sel_hi:[0,1,0]
	v_pk_fma_f32 v[92:93], v[208:209], v[96:97], v[206:207] op_sel_hi:[0,1,0]
	v_pk_fma_f32 v[94:95], v[208:209], v[112:113], v[206:207] op_sel_hi:[0,1,0]
	v_pk_fma_f32 v[96:97], v[208:209], v[126:127], v[206:207] op_sel_hi:[0,1,0]
	v_pk_fma_f32 v[84:85], v[202:203], v[84:85], v[204:205] op_sel_hi:[0,1,0]
	v_pk_fma_f32 v[106:107], v[202:203], v[86:87], v[204:205] op_sel_hi:[0,1,0]
	v_pk_fma_f32 v[108:109], v[202:203], v[88:89], v[204:205] op_sel_hi:[0,1,0]
	v_pk_fma_f32 v[90:91], v[202:203], v[90:91], v[204:205] op_sel_hi:[0,1,0]
	v_cvt_pk_bf16_f32 v86, v82, v83
	v_cvt_pk_bf16_f32 v87, v92, v93
	v_cvt_pk_bf16_f32 v88, v94, v95
	v_cvt_pk_bf16_f32 v89, v96, v97
	v_cvt_pk_bf16_f32 v82, v84, v85
	v_cvt_pk_bf16_f32 v83, v106, v107
	v_cvt_pk_bf16_f32 v84, v108, v109
	v_cvt_pk_bf16_f32 v85, v90, v91
	ds_read_b128 v[90:93], v110
	ds_read_b128 v[94:97], v110 offset:16
	ds_read_b128 v[106:109], v110 offset:32
	s_nop 0
	ds_read_b128 v[110:113], v110 offset:48
	v_lshlrev_b32_e32 v122, 16, v118
	v_and_b32_e32 v123, 0xffff0000, v118
	v_lshlrev_b32_e32 v118, 16, v119
	v_and_b32_e32 v119, 0xffff0000, v119
	v_lshlrev_b32_e32 v124, 16, v120
	v_and_b32_e32 v125, 0xffff0000, v120
	v_lshlrev_b32_e32 v120, 16, v121
	v_and_b32_e32 v121, 0xffff0000, v121
	v_lshlrev_b32_e32 v126, 16, v114
	v_and_b32_e32 v127, 0xffff0000, v114
	v_lshlrev_b32_e32 v114, 16, v115
	v_and_b32_e32 v115, 0xffff0000, v115
	v_lshlrev_b32_e32 v128, 16, v116
	v_and_b32_e32 v129, 0xffff0000, v116
	v_lshlrev_b32_e32 v116, 16, v117
	v_and_b32_e32 v117, 0xffff0000, v117
	v_pk_mul_f32 v[130:131], v[64:65], s[20:21] op_sel_hi:[1,0]
	v_pk_fma_f32 v[132:133], v[132:133], s[16:17], v[196:197] op_sel_hi:[1,0,0] neg_lo:[1,0,0] neg_hi:[1,0,0]
	v_pk_mul_f32 v[64:65], v[60:61], v[64:65]
	v_pk_mul_f32 v[56:57], v[56:57], v[132:133]
	s_waitcnt lgkmcnt(3)
; #define GAS __attribute__((address_space(1)))
; __device__ __forceinline__ float fexp2(float x) { return __builtin_amdgcn_exp2f(x); }
; __device__ __forceinline__ float frcp(float x) { return __builtin_amdgcn_rcpf(x); }
;     __device__ __forceinline__ void operator()(const af4 (&acc)[2][2][4][2], const pg8::Unit& u, int wr_, int wc_, int fr_, int fq_) const {
;     ...
;             for (int m = 0; m < 4; ++m) {
;                 if (ai == 0 && m == 0) load_raw(1);
;                 const int it = wr * 64 + m * 16 + fr;
;                 bf16x8 wf[4];
; #pragma unroll
;                 for (int ks = 0; ks < 4; ++ks) wf[ks] = *(const GAS bf16x8*)(wsg + (size_t)it * 128 + 32 * ks + 8 * fq);
;                 const float bsi = bs[grp * 128 + it];
;                 af4 vm[2] = {(af4){bsi, bsi, bsi, bsi}, (af4){bsi, bsi, bsi, bsi}};
; #pragma unroll
;                 for (int ks = 0; ks < 4; ++ks) {
; #pragma unroll
;                     for (int n = 0; n < 2; ++n) vm[n] = __builtin_amdgcn_mfma_f32_16x16x32_bf16(av[n][ks], wf[ks], vm[n], 0, 0, 0);
;                 }
;                 float o[8];
; #pragma unroll
;                 for (int n = 0; n < 2; ++n)
; #pragma unroll
;                     for (int e = 0; e < 4; e += 2) {
;                         const f32x2 uu = {acc[ai][0][m][n][e], acc[ai][0][m][n][e + 1]}, gg = {acc[ai][1][m][n][e], acc[ai][1][m][n][e + 1]}, vv = {vm[n][e], vm[n][e + 1]};
;                         const f32x2 ar = uu * (uu * uu * (-2.302208198f * 0.044715f) + (-2.302208198f));
;                         const f32x2 gs = gg * (-1.4426950408889634f);
;                         const f32x2 ea = {fexp2(ar.x), fexp2(ar.y)}, eb = {fexp2(gs.x), fexp2(gs.y)};
;                         const f32x2 q = eb + 1.0f, den = ea * q + q;
;                         const f32x2 r = {frcp(den.x), frcp(den.y)};
;                         const f32x2 w = (uu * gg) * vv * r;
;                         o[4 * n + e] = w.x; o[4 * n + e + 1] = w.y; }
	v_pk_fma_f32 v[122:123], v[92:93], v[122:123], v[90:91]
	s_waitcnt lgkmcnt(2)
	v_pk_fma_f32 v[118:119], v[96:97], v[118:119], v[94:95]
	s_waitcnt lgkmcnt(1)
	v_pk_fma_f32 v[124:125], v[108:109], v[124:125], v[106:107]
	s_waitcnt lgkmcnt(0)
	v_pk_fma_f32 v[120:121], v[112:113], v[120:121], v[110:111]
	v_pk_fma_f32 v[90:91], v[92:93], v[126:127], v[90:91]
	v_pk_fma_f32 v[92:93], v[96:97], v[114:115], v[94:95]
	v_pk_fma_f32 v[94:95], v[108:109], v[128:129], v[106:107]
	v_pk_fma_f32 v[96:97], v[112:113], v[116:117], v[110:111]
	v_pk_fma_f32 v[106:107], v[208:209], v[122:123], v[206:207] op_sel_hi:[0,1,0]
	v_pk_fma_f32 v[108:109], v[208:209], v[118:119], v[206:207] op_sel_hi:[0,1,0]
	v_pk_fma_f32 v[110:111], v[208:209], v[124:125], v[206:207] op_sel_hi:[0,1,0]
	v_pk_fma_f32 v[112:113], v[208:209], v[120:121], v[206:207] op_sel_hi:[0,1,0]
	v_pk_fma_f32 v[114:115], v[202:203], v[90:91], v[204:205] op_sel_hi:[0,1,0]
	v_pk_fma_f32 v[116:117], v[202:203], v[92:93], v[204:205] op_sel_hi:[0,1,0]
	v_pk_fma_f32 v[118:119], v[202:203], v[94:95], v[204:205] op_sel_hi:[0,1,0]
	v_pk_fma_f32 v[120:121], v[202:203], v[96:97], v[204:205] op_sel_hi:[0,1,0]
	v_cvt_pk_bf16_f32 v90, v106, v107
	v_cvt_pk_bf16_f32 v91, v108, v109
	v_cvt_pk_bf16_f32 v92, v110, v111
	v_cvt_pk_bf16_f32 v93, v112, v113
	v_cvt_pk_bf16_f32 v94, v114, v115
	v_cvt_pk_bf16_f32 v95, v116, v117
	v_cvt_pk_bf16_f32 v96, v118, v119
	v_cvt_pk_bf16_f32 v97, v120, v121
	global_load_dword v106, v[200:201], off
	global_load_dwordx4 v[110:113], v[214:215], off
	global_load_dwordx4 v[114:117], v[214:215], off offset:64
	global_load_dwordx4 v[118:121], v[214:215], off offset:128
	global_load_dwordx4 v[122:125], v[214:215], off offset:192
	v_pk_mul_f32 v[108:109], v[60:61], v[60:61]
	v_pk_mul_f32 v[126:127], v[58:59], v[58:59]
	v_pk_mul_f32 v[128:129], v[62:63], s[20:21] op_sel_hi:[1,0]
	v_pk_fma_f32 v[52:53], v[126:127], s[16:17], v[196:197] op_sel_hi:[1,0,0] neg_lo:[1,0,0] neg_hi:[1,0,0]
	v_pk_fma_f32 v[108:109], v[108:109], s[16:17], v[196:197] op_sel_hi:[1,0,0] neg_lo:[1,0,0] neg_hi:[1,0,0]
	v_exp_f32_e32 v126, v128
	v_exp_f32_e32 v127, v129
	v_exp_f32_e32 v128, v130
	v_exp_f32_e32 v129, v131
	v_pk_fma_f32 v[130:131], v[134:135], s[16:17], v[196:197] op_sel_hi:[1,0,0] neg_lo:[1,0,0] neg_hi:[1,0,0]
	v_exp_f32_e32 v134, v136
	v_exp_f32_e32 v135, v137
	v_exp_f32_e32 v136, v50
	v_exp_f32_e32 v137, v51
	v_pk_mul_f32 v[50:51], v[58:59], v[52:53]
	v_pk_mul_f32 v[52:53], v[60:61], v[108:109]
	v_pk_mul_f32 v[62:63], v[58:59], v[62:63]
	v_pk_mul_f32 v[54:55], v[54:55], v[130:131]
	v_exp_f32_e32 v58, v50
	v_exp_f32_e32 v59, v51
	v_exp_f32_e32 v60, v52
	v_exp_f32_e32 v61, v53
	v_exp_f32_e32 v130, v54
	v_exp_f32_e32 v131, v55
	v_exp_f32_e32 v132, v56
	v_exp_f32_e32 v133, v57
	v_pk_add_f32 v[126:127], v[126:127], 1.0 op_sel_hi:[1,0]
	v_pk_add_f32 v[128:129], v[128:129], 1.0 op_sel_hi:[1,0]
	v_pk_add_f32 v[134:135], v[134:135], 1.0 op_sel_hi:[1,0]
	v_pk_add_f32 v[136:137], v[136:137], 1.0 op_sel_hi:[1,0]
	v_pk_fma_f32 v[58:59], v[58:59], v[126:127], v[126:127]
	v_pk_fma_f32 v[60:61], v[60:61], v[128:129], v[128:129]
	v_rcp_f32_e32 v58, v58
	v_rcp_f32_e32 v59, v59
	v_rcp_f32_e32 v60, v60
	v_rcp_f32_e32 v61, v61
	s_waitcnt vmcnt(4)
	v_mov_b32_e32 v107, v106
	v_mov_b32_e32 v108, v106
	v_mov_b32_e32 v109, v106
	s_waitcnt vmcnt(3)
	s_nop 0
	v_mfma_f32_16x16x32_bf16 v[50:53], v[70:73], v[110:113], v[106:109]
	v_mfma_f32_16x16x32_bf16 v[54:57], v[66:69], v[110:113], v[106:109]
	v_mad_i64_i32 v[110:111], s[26:27], v99, s61, v[198:199]
	v_lshl_add_u64 v[110:111], v[110:111], 0, s[40:41]
	s_waitcnt vmcnt(2)
	v_mfma_f32_16x16x32_bf16 v[50:53], v[78:81], v[114:117], v[50:53]
	v_fma_f32 v106, v130, v134, v134
	v_fma_f32 v107, v131, v135, v135
	v_pk_fma_f32 v[108:109], v[132:133], v[136:137], v[136:137]
	v_rcp_f32_e32 v106, v106
	v_mfma_f32_16x16x32_bf16 v[54:57], v[74:77], v[114:117], v[54:57]
	v_rcp_f32_e32 v107, v107
	v_rcp_f32_e32 v108, v108
	v_rcp_f32_e32 v109, v109
	s_waitcnt vmcnt(1)
	v_mfma_f32_16x16x32_bf16 v[50:53], v[86:89], v[118:121], v[50:53]
	v_lshl_add_u64 v[110:111], v[110:111], 0, s[6:7]
	v_lshl_add_u64 v[110:111], v[110:111], 0, v[186:187]
	v_pk_mul_f32 v[112:113], v[46:47], s[20:21] op_sel_hi:[1,0]
	v_mfma_f32_16x16x32_bf16 v[54:57], v[82:85], v[118:121], v[54:57]
	v_mul_f32_e64 v114, v48, s20
	v_mul_f32_e64 v115, v49, s20
	v_pk_mul_f32 v[116:117], v[40:41], v[40:41]
	v_pk_mul_f32 v[118:119], v[38:39], v[38:39]
	s_waitcnt vmcnt(0)
; #define GAS __attribute__((address_space(1)))
; __device__ __forceinline__ v4u pack8(const float (&f)[8]) { v4u w; w.x = pk2(f[0], f[1]); w.y = pk2(f[2], f[3]); w.z = pk2(f[4], f[5]); w.w = pk2(f[6], f[7]); return w; }
; __device__ __forceinline__ float fexp2(float x) { return __builtin_amdgcn_exp2f(x); }
; __device__ __forceinline__ float frcp(float x) { return __builtin_amdgcn_rcpf(x); }
;     __device__ __forceinline__ void operator()(const af4 (&acc)[2][2][4][2], const pg8::Unit& u, int wr_, int wc_, int fr_, int fq_) const {
;     ...
;             for (int m = 0; m < 4; ++m) {
;                 if (ai == 0 && m == 0) load_raw(1);
;                 const int it = wr * 64 + m * 16 + fr;
;                 bf16x8 wf[4];
; #pragma unroll
;                 for (int ks = 0; ks < 4; ++ks) wf[ks] = *(const GAS bf16x8*)(wsg + (size_t)it * 128 + 32 * ks + 8 * fq);
;                 const float bsi = bs[grp * 128 + it];
;                 af4 vm[2] = {(af4){bsi, bsi, bsi, bsi}, (af4){bsi, bsi, bsi, bsi}};
; #pragma unroll
;                 for (int ks = 0; ks < 4; ++ks) {
; #pragma unroll
;                     for (int n = 0; n < 2; ++n) vm[n] = __builtin_amdgcn_mfma_f32_16x16x32_bf16(av[n][ks], wf[ks], vm[n], 0, 0, 0);
;                 }
;                 float o[8];
; #pragma unroll
;                 for (int n = 0; n < 2; ++n)
; #pragma unroll
;                     for (int e = 0; e < 4; e += 2) {
;                         const f32x2 uu = {acc[ai][0][m][n][e], acc[ai][0][m][n][e + 1]}, gg = {acc[ai][1][m][n][e], acc[ai][1][m][n][e + 1]}, vv = {vm[n][e], vm[n][e + 1]};
;                         const f32x2 ar = uu * (uu * uu * (-2.302208198f * 0.044715f) + (-2.302208198f));
;                         const f32x2 gs = gg * (-1.4426950408889634f);
;                         const f32x2 ea = {fexp2(ar.x), fexp2(ar.y)}, eb = {fexp2(gs.x), fexp2(gs.y)};
;                         const f32x2 q = eb + 1.0f, den = ea * q + q;
;                         const f32x2 r = {frcp(den.x), frcp(den.y)};
;                         const f32x2 w = (uu * gg) * vv * r;
;                         o[4 * n + e] = w.x; o[4 * n + e + 1] = w.y; }
;                 *(GAS v4u*)(Y + (size_t)(tok0 + it) * CW + chbase + 32 * wc + 8 * fq) = pack8(o);
;             }
	v_mfma_f32_16x16x32_bf16 v[50:53], v[90:93], v[122:125], v[50:53]
	v_mul_f32_e64 v120, v34, s20
	v_mul_f32_e64 v121, v35, s20
	v_pk_fma_f32 v[116:117], v[116:117], s[16:17], v[196:197] op_sel_hi:[1,0,0] neg_lo:[1,0,0] neg_hi:[1,0,0]
	v_pk_mul_f32 v[46:47], v[42:43], v[46:47]
	v_mfma_f32_16x16x32_bf16 v[54:57], v[94:97], v[122:125], v[54:57]
	v_mul_f32_e64 v122, v38, v34
	v_mul_f32_e64 v123, v39, v35
	s_nop 0
	v_pk_mul_f32 v[50:51], v[62:63], v[50:51]
	v_pk_mul_f32 v[52:53], v[64:65], v[52:53]
	v_pk_mul_f32 v[50:51], v[58:59], v[50:51]
	v_pk_mul_f32 v[52:53], v[60:61], v[52:53]
	s_nop 0
	v_pk_mul_f32 v[54:55], v[138:139], v[54:55]
	v_pk_mul_f32 v[56:57], v[140:141], v[56:57]
	v_pk_mul_f32 v[54:55], v[106:107], v[54:55]
	v_pk_mul_f32 v[56:57], v[108:109], v[56:57]
	v_cvt_pk_bf16_f32 v50, v50, v51
	v_cvt_pk_bf16_f32 v51, v52, v53
	v_cvt_pk_bf16_f32 v52, v54, v55
	v_pk_mul_f32 v[34:35], v[36:37], s[20:21] op_sel_hi:[1,0]
	v_cvt_pk_bf16_f32 v53, v56, v57
	global_store_dwordx4 v[110:111], v[50:53], off
	s_nop 0
	s_nop 0
	ds_read_b128 v[54:57], v189 offset:0
	ds_read_b128 v[58:61], v189 offset:1024
	ds_read_b128 v[62:65], v189 offset:2048
	ds_read_b128 v[106:109], v189 offset:3072
	v_pk_mul_f32 v[52:53], v[44:45], v[44:45]
	v_pk_mul_f32 v[110:111], v[42:43], v[42:43]
	v_pk_mul_f32 v[124:125], v[40:41], v[36:37]
	v_pk_fma_f32 v[36:37], v[110:111], s[16:17], v[196:197] op_sel_hi:[1,0,0] neg_lo:[1,0,0] neg_hi:[1,0,0]
	v_pk_fma_f32 v[52:53], v[52:53], s[16:17], v[196:197] op_sel_hi:[1,0,0] neg_lo:[1,0,0] neg_hi:[1,0,0]
	v_exp_f32_e32 v110, v112
	v_exp_f32_e32 v111, v113
	v_exp_f32_e32 v112, v114
	v_exp_f32_e32 v113, v115
	v_pk_fma_f32 v[114:115], v[118:119], s[16:17], v[196:197] op_sel_hi:[1,0,0] neg_lo:[1,0,0] neg_hi:[1,0,0]
	v_exp_f32_e32 v118, v120
	v_exp_f32_e32 v119, v121
	v_exp_f32_e32 v120, v34
	v_exp_f32_e32 v121, v35
	v_pk_mul_f32 v[34:35], v[42:43], v[36:37]
	v_pk_mul_f32 v[36:37], v[44:45], v[52:53]
	v_pk_mul_f32 v[48:49], v[44:45], v[48:49]
	v_pk_mul_f32 v[38:39], v[38:39], v[114:115]
	v_pk_mul_f32 v[40:41], v[40:41], v[116:117]
	v_exp_f32_e32 v42, v34
	v_exp_f32_e32 v43, v35
	v_exp_f32_e32 v44, v36
	v_exp_f32_e32 v45, v37
	v_exp_f32_e32 v114, v38
	v_exp_f32_e32 v115, v39
	v_exp_f32_e32 v116, v40
	v_exp_f32_e32 v117, v41
	v_pk_add_f32 v[110:111], v[110:111], 1.0 op_sel_hi:[1,0]
	v_pk_add_f32 v[112:113], v[112:113], 1.0 op_sel_hi:[1,0]
	v_pk_add_f32 v[118:119], v[118:119], 1.0 op_sel_hi:[1,0]
	v_pk_add_f32 v[120:121], v[120:121], 1.0 op_sel_hi:[1,0]
	v_pk_fma_f32 v[42:43], v[42:43], v[110:111], v[110:111]
	v_pk_fma_f32 v[44:45], v[44:45], v[112:113], v[112:113]
	v_rcp_f32_e32 v42, v42
	v_rcp_f32_e32 v43, v43
	v_rcp_f32_e32 v44, v44
	v_rcp_f32_e32 v45, v45
	v_mov_b32_e32 v50, v179
	v_mov_b32_e32 v51, v50
	v_mov_b32_e32 v52, v50
	v_mov_b32_e32 v53, v50
	s_waitcnt lgkmcnt(3)
	s_nop 0
	v_mfma_f32_16x16x32_bf16 v[34:37], v[70:73], v[54:57], v[50:53]
	v_mfma_f32_16x16x32_bf16 v[38:41], v[66:69], v[54:57], v[50:53]
	v_add_u32_e32 v54, s23, v212
	v_mad_i64_i32 v[54:55], s[26:27], v54, s61, v[198:199]
	s_waitcnt lgkmcnt(2)
	v_mfma_f32_16x16x32_bf16 v[34:37], v[78:81], v[58:61], v[34:37]
	v_fma_f32 v50, v114, v118, v118
	v_fma_f32 v51, v115, v119, v119
	v_pk_fma_f32 v[52:53], v[116:117], v[120:121], v[120:121]
	v_rcp_f32_e32 v50, v50
	v_mfma_f32_16x16x32_bf16 v[38:41], v[74:77], v[58:61], v[38:41]
	v_rcp_f32_e32 v51, v51
	v_rcp_f32_e32 v52, v52
	v_rcp_f32_e32 v53, v53
	s_waitcnt lgkmcnt(1)
	v_mfma_f32_16x16x32_bf16 v[34:37], v[86:89], v[62:65], v[34:37]
	v_lshl_add_u64 v[54:55], v[54:55], 0, s[40:41]
	v_lshl_add_u64 v[54:55], v[54:55], 0, s[6:7]
	v_lshl_add_u64 v[54:55], v[54:55], 0, v[186:187]
	v_mfma_f32_16x16x32_bf16 v[38:41], v[82:85], v[62:65], v[38:41]
	v_mul_f32_e64 v56, v30, s20
	v_mul_f32_e64 v57, v31, s20
	v_pk_mul_f32 v[58:59], v[32:33], s[20:21] op_sel_hi:[1,0]
	v_pk_mul_f32 v[60:61], v[24:25], v[24:25]
	s_waitcnt lgkmcnt(0)
	v_mfma_f32_16x16x32_bf16 v[34:37], v[90:93], v[106:109], v[34:37]
	v_mul_f32_e64 v62, v22, v22
	v_mul_f32_e64 v63, v23, v23
	v_pk_mul_f32 v[64:65], v[18:19], s[20:21] op_sel_hi:[1,0]
	v_pk_fma_f32 v[60:61], v[60:61], s[16:17], v[196:197] op_sel_hi:[1,0,0] neg_lo:[1,0,0] neg_hi:[1,0,0]
	v_mfma_f32_16x16x32_bf16 v[38:41], v[94:97], v[106:109], v[38:41]
	v_mul_f32_e64 v106, v24, v20
	v_mul_f32_e64 v107, v25, v21
	s_nop 0
	v_pk_mul_f32 v[34:35], v[46:47], v[34:35]
	v_pk_mul_f32 v[36:37], v[48:49], v[36:37]
	v_pk_mul_f32 v[34:35], v[42:43], v[34:35]
	v_pk_mul_f32 v[36:37], v[44:45], v[36:37]
	s_nop 0
	v_pk_mul_f32 v[38:39], v[122:123], v[38:39]
	v_pk_mul_f32 v[40:41], v[124:125], v[40:41]
	v_pk_mul_f32 v[38:39], v[50:51], v[38:39]
	v_pk_mul_f32 v[40:41], v[52:53], v[40:41]
	v_cvt_pk_bf16_f32 v34, v34, v35
	v_cvt_pk_bf16_f32 v35, v36, v37
	v_cvt_pk_bf16_f32 v36, v38, v39
	v_pk_mul_f32 v[30:31], v[26:27], v[30:31]
	v_cvt_pk_bf16_f32 v37, v40, v41
	global_store_dwordx4 v[54:55], v[34:37], off
	s_nop 0
	s_nop 0
	ds_read_b128 v[38:41], v189 offset:4096
	ds_read_b128 v[42:45], v189 offset:5120
	ds_read_b128 v[46:49], v189 offset:6144
	ds_read_b128 v[50:53], v189 offset:7168
	v_pk_mul_f32 v[36:37], v[28:29], v[28:29]
	v_pk_mul_f32 v[54:55], v[26:27], v[26:27]
	v_pk_mul_f32 v[102:103], v[22:23], v[18:19]
	v_pk_mul_f32 v[18:19], v[20:21], s[20:21] op_sel_hi:[1,0]
	v_pk_fma_f32 v[20:21], v[54:55], s[16:17], v[196:197] op_sel_hi:[1,0,0] neg_lo:[1,0,0] neg_hi:[1,0,0]
	v_pk_fma_f32 v[36:37], v[36:37], s[16:17], v[196:197] op_sel_hi:[1,0,0] neg_lo:[1,0,0] neg_hi:[1,0,0]
	v_exp_f32_e32 v54, v56
	v_exp_f32_e32 v55, v57
	v_exp_f32_e32 v56, v58
	v_exp_f32_e32 v57, v59
	v_pk_fma_f32 v[58:59], v[62:63], s[16:17], v[196:197] op_sel_hi:[1,0,0] neg_lo:[1,0,0] neg_hi:[1,0,0]
	v_exp_f32_e32 v62, v64
	v_exp_f32_e32 v63, v65
	v_exp_f32_e32 v64, v18
	v_exp_f32_e32 v65, v19
	v_pk_mul_f32 v[18:19], v[26:27], v[20:21]
	v_pk_mul_f32 v[20:21], v[28:29], v[36:37]
	v_pk_mul_f32 v[32:33], v[28:29], v[32:33]
	v_pk_mul_f32 v[22:23], v[22:23], v[58:59]
	v_pk_mul_f32 v[24:25], v[24:25], v[60:61]
	v_exp_f32_e32 v26, v18
	v_exp_f32_e32 v27, v19
	v_exp_f32_e32 v28, v20
	v_exp_f32_e32 v29, v21
	v_exp_f32_e32 v58, v22
	v_exp_f32_e32 v59, v23
	v_exp_f32_e32 v60, v24
	v_exp_f32_e32 v61, v25
	v_pk_add_f32 v[54:55], v[54:55], 1.0 op_sel_hi:[1,0]
	v_pk_add_f32 v[56:57], v[56:57], 1.0 op_sel_hi:[1,0]
	v_pk_add_f32 v[62:63], v[62:63], 1.0 op_sel_hi:[1,0]
	v_pk_add_f32 v[64:65], v[64:65], 1.0 op_sel_hi:[1,0]
	v_pk_fma_f32 v[26:27], v[26:27], v[54:55], v[54:55]
	v_pk_fma_f32 v[28:29], v[28:29], v[56:57], v[56:57]
	v_rcp_f32_e32 v26, v26
	v_rcp_f32_e32 v27, v27
	v_rcp_f32_e32 v28, v28
	v_rcp_f32_e32 v29, v29
	v_mov_b32_e32 v34, v181
	v_mov_b32_e32 v35, v34
	v_mov_b32_e32 v36, v34
	v_mov_b32_e32 v37, v34
	s_waitcnt lgkmcnt(3)
; #define GAS __attribute__((address_space(1)))
; __device__ __forceinline__ v4u pack8(const float (&f)[8]) { v4u w; w.x = pk2(f[0], f[1]); w.y = pk2(f[2], f[3]); w.z = pk2(f[4], f[5]); w.w = pk2(f[6], f[7]); return w; }
; template <class Epi, class Sched, bool ALIGN_EPI = false, bool SP2 = false>
; __device__ __forceinline__ void gemm_phase(PG8_LAS unsigned char* lds, const Gemm g, const Sched& S, const Epi& E) {
;     ...
;         E(acc, cur, wr, wc, fr, fq);
;         if (!has_next) break;
;     __device__ __forceinline__ void operator()(const af4 (&acc)[2][2][4][2], const pg8::Unit& u, int wr_, int wc_, int fr_, int fq_) const {
;     ...
;             for (int m = 0; m < 4; ++m) {
;                 if (ai == 0 && m == 0) load_raw(1);
;                 const int it = wr * 64 + m * 16 + fr;
;                 bf16x8 wf[4];
; #pragma unroll
;                 for (int ks = 0; ks < 4; ++ks) wf[ks] = *(const GAS bf16x8*)(wsg + (size_t)it * 128 + 32 * ks + 8 * fq);
;                 const float bsi = bs[grp * 128 + it];
;                 af4 vm[2] = {(af4){bsi, bsi, bsi, bsi}, (af4){bsi, bsi, bsi, bsi}};
; #pragma unroll
;                 for (int ks = 0; ks < 4; ++ks) {
; #pragma unroll
;                     for (int n = 0; n < 2; ++n) vm[n] = __builtin_amdgcn_mfma_f32_16x16x32_bf16(av[n][ks], wf[ks], vm[n], 0, 0, 0);
;                 }
;                 float o[8];
; #pragma unroll
;                 for (int n = 0; n < 2; ++n)
; #pragma unroll
;                     for (int e = 0; e < 4; e += 2) {
;                         const f32x2 uu = {acc[ai][0][m][n][e], acc[ai][0][m][n][e + 1]}, gg = {acc[ai][1][m][n][e], acc[ai][1][m][n][e + 1]}, vv = {vm[n][e], vm[n][e + 1]};
;                         const f32x2 ar = uu * (uu * uu * (-2.302208198f * 0.044715f) + (-2.302208198f));
;                         const f32x2 gs = gg * (-1.4426950408889634f);
;                         const f32x2 ea = {fexp2(ar.x), fexp2(ar.y)}, eb = {fexp2(gs.x), fexp2(gs.y)};
;                         const f32x2 q = eb + 1.0f, den = ea * q + q;
;                         const f32x2 r = {frcp(den.x), frcp(den.y)};
;                         const f32x2 w = (uu * gg) * vv * r;
;                         o[4 * n + e] = w.x; o[4 * n + e + 1] = w.y; }
;                 *(GAS v4u*)(Y + (size_t)(tok0 + it) * CW + chbase + 32 * wc + 8 * fq) = pack8(o);
;             }
	s_nop 0
	v_mfma_f32_16x16x32_bf16 v[18:21], v[70:73], v[38:41], v[34:37]
	v_mfma_f32_16x16x32_bf16 v[22:25], v[66:69], v[38:41], v[34:37]
	v_add_u32_e32 v38, s23, v98
	v_mad_i64_i32 v[38:39], s[26:27], v38, s61, v[198:199]
	s_waitcnt lgkmcnt(2)
	v_mfma_f32_16x16x32_bf16 v[18:21], v[78:81], v[42:45], v[18:21]
	v_fma_f32 v34, v58, v62, v62
	v_fma_f32 v35, v59, v63, v63
	v_pk_fma_f32 v[36:37], v[60:61], v[64:65], v[64:65]
	v_rcp_f32_e32 v34, v34
	v_mfma_f32_16x16x32_bf16 v[22:25], v[74:77], v[42:45], v[22:25]
	v_rcp_f32_e32 v35, v35
	v_rcp_f32_e32 v36, v36
	v_rcp_f32_e32 v37, v37
	s_waitcnt lgkmcnt(1)
	v_mfma_f32_16x16x32_bf16 v[18:21], v[86:89], v[46:49], v[18:21]
	v_lshl_add_u64 v[38:39], v[38:39], 0, s[40:41]
	v_lshl_add_u64 v[38:39], v[38:39], 0, s[6:7]
	v_lshl_add_u64 v[38:39], v[38:39], 0, v[186:187]
	v_mfma_f32_16x16x32_bf16 v[22:25], v[82:85], v[46:49], v[22:25]
	v_mul_f32_e64 v40, v14, s20
	v_mul_f32_e64 v41, v15, s20
	v_pk_mul_f32 v[42:43], v[16:17], s[20:21] op_sel_hi:[1,0]
	v_pk_mul_f32 v[44:45], v[8:9], v[8:9]
	s_waitcnt lgkmcnt(0)
	v_mfma_f32_16x16x32_bf16 v[18:21], v[90:93], v[50:53], v[18:21]
	v_mul_f32_e64 v46, v6, v6
	v_mul_f32_e64 v47, v7, v7
	v_pk_mul_f32 v[48:49], v[2:3], s[20:21] op_sel_hi:[1,0]
	v_pk_fma_f32 v[44:45], v[44:45], s[16:17], v[196:197] op_sel_hi:[1,0,0] neg_lo:[1,0,0] neg_hi:[1,0,0]
	v_mfma_f32_16x16x32_bf16 v[22:25], v[94:97], v[50:53], v[22:25]
	v_mul_f32_e64 v50, v6, v2
	v_mul_f32_e64 v51, v7, v3
	s_nop 0
	v_pk_mul_f32 v[18:19], v[30:31], v[18:19]
	v_pk_mul_f32 v[20:21], v[32:33], v[20:21]
	v_pk_mul_f32 v[18:19], v[26:27], v[18:19]
	v_pk_mul_f32 v[20:21], v[28:29], v[20:21]
	s_nop 0
	v_pk_mul_f32 v[22:23], v[102:103], v[22:23]
	v_pk_mul_f32 v[24:25], v[106:107], v[24:25]
	v_pk_mul_f32 v[22:23], v[34:35], v[22:23]
	v_pk_mul_f32 v[24:25], v[36:37], v[24:25]
	v_cvt_pk_bf16_f32 v18, v18, v19
	v_cvt_pk_bf16_f32 v19, v20, v21
	v_cvt_pk_bf16_f32 v20, v22, v23
	v_pk_mul_f32 v[2:3], v[4:5], s[20:21] op_sel_hi:[1,0]
	v_cvt_pk_bf16_f32 v21, v24, v25
	global_store_dwordx4 v[38:39], v[18:21], off
	s_nop 0
	s_nop 0
	ds_read_b128 v[22:25], v189 offset:8192
	ds_read_b128 v[26:29], v189 offset:9216
	ds_read_b128 v[30:33], v189 offset:10240
	ds_read_b128 v[34:37], v189 offset:11264
	v_pk_mul_f32 v[20:21], v[12:13], v[12:13]
	v_pk_mul_f32 v[38:39], v[10:11], v[10:11]
	v_pk_mul_f32 v[52:53], v[8:9], v[4:5]
	v_pk_fma_f32 v[4:5], v[38:39], s[16:17], v[196:197] op_sel_hi:[1,0,0] neg_lo:[1,0,0] neg_hi:[1,0,0]
	v_pk_fma_f32 v[20:21], v[20:21], s[16:17], v[196:197] op_sel_hi:[1,0,0] neg_lo:[1,0,0] neg_hi:[1,0,0]
	v_exp_f32_e32 v38, v40
	v_exp_f32_e32 v39, v41
	v_exp_f32_e32 v40, v42
	v_exp_f32_e32 v41, v43
	v_pk_fma_f32 v[42:43], v[46:47], s[16:17], v[196:197] op_sel_hi:[1,0,0] neg_lo:[1,0,0] neg_hi:[1,0,0]
	v_exp_f32_e32 v46, v48
	v_exp_f32_e32 v47, v49
	v_exp_f32_e32 v48, v2
	v_exp_f32_e32 v49, v3
	v_pk_mul_f32 v[2:3], v[10:11], v[4:5]
	v_pk_mul_f32 v[4:5], v[12:13], v[20:21]
	v_pk_mul_f32 v[14:15], v[10:11], v[14:15]
	v_pk_mul_f32 v[16:17], v[12:13], v[16:17]
	v_pk_mul_f32 v[6:7], v[6:7], v[42:43]
	v_pk_mul_f32 v[8:9], v[8:9], v[44:45]
	v_exp_f32_e32 v10, v2
	v_exp_f32_e32 v11, v3
	v_exp_f32_e32 v12, v4
	v_exp_f32_e32 v13, v5
	v_exp_f32_e32 v42, v6
	v_exp_f32_e32 v43, v7
	v_exp_f32_e32 v44, v8
	v_exp_f32_e32 v45, v9
	v_pk_add_f32 v[38:39], v[38:39], 1.0 op_sel_hi:[1,0]
	v_pk_add_f32 v[40:41], v[40:41], 1.0 op_sel_hi:[1,0]
	v_pk_add_f32 v[46:47], v[46:47], 1.0 op_sel_hi:[1,0]
	v_pk_add_f32 v[48:49], v[48:49], 1.0 op_sel_hi:[1,0]
	v_pk_fma_f32 v[10:11], v[10:11], v[38:39], v[38:39]
	v_pk_fma_f32 v[12:13], v[12:13], v[40:41], v[40:41]
	v_rcp_f32_e32 v10, v10
	v_rcp_f32_e32 v11, v11
	v_rcp_f32_e32 v12, v12
	v_rcp_f32_e32 v13, v13
	v_mov_b32_e32 v18, v183
	v_mov_b32_e32 v19, v18
	v_mov_b32_e32 v20, v18
	v_mov_b32_e32 v21, v18
	s_waitcnt lgkmcnt(3)
	s_nop 0
	v_mfma_f32_16x16x32_bf16 v[2:5], v[70:73], v[22:25], v[18:21]
	v_mfma_f32_16x16x32_bf16 v[6:9], v[66:69], v[22:25], v[18:21]
	v_add_u32_e32 v22, s23, v100
	v_mad_i64_i32 v[22:23], s[4:5], v22, s61, v[198:199]
	s_waitcnt lgkmcnt(2)
	v_mfma_f32_16x16x32_bf16 v[2:5], v[78:81], v[26:29], v[2:5]
	v_fma_f32 v18, v42, v46, v46
	v_fma_f32 v19, v43, v47, v47
	v_pk_fma_f32 v[20:21], v[44:45], v[48:49], v[48:49]
	v_rcp_f32_e32 v18, v18
	v_mfma_f32_16x16x32_bf16 v[6:9], v[74:77], v[26:29], v[6:9]
	v_rcp_f32_e32 v19, v19
	v_rcp_f32_e32 v20, v20
	v_rcp_f32_e32 v21, v21
	s_waitcnt lgkmcnt(1)
	v_mfma_f32_16x16x32_bf16 v[2:5], v[86:89], v[30:33], v[2:5]
	v_lshl_add_u64 v[22:23], v[22:23], 0, s[40:41]
	v_lshl_add_u64 v[22:23], v[22:23], 0, s[6:7]
	v_lshl_add_u64 v[22:23], v[22:23], 0, v[186:187]
	v_mfma_f32_16x16x32_bf16 v[6:9], v[82:85], v[30:33], v[6:9]
	s_mov_b64 s[4:5], -1
	s_waitcnt lgkmcnt(0)
	v_mfma_f32_16x16x32_bf16 v[2:5], v[90:93], v[34:37], v[2:5]
	v_mfma_f32_16x16x32_bf16 v[6:9], v[94:97], v[34:37], v[6:9]
	s_nop 6
	v_mul_f32_e64 v2, v14, v2
	v_mul_f32_e64 v3, v15, v3
	v_pk_mul_f32 v[4:5], v[16:17], v[4:5]
	v_pk_mul_f32 v[6:7], v[50:51], v[6:7]
	v_pk_mul_f32 v[8:9], v[52:53], v[8:9]
	v_pk_mul_f32 v[2:3], v[10:11], v[2:3]
	v_pk_mul_f32 v[4:5], v[12:13], v[4:5]
	v_pk_mul_f32 v[6:7], v[18:19], v[6:7]
	v_pk_mul_f32 v[8:9], v[20:21], v[8:9]
	v_cvt_pk_bf16_f32 v2, v2, v3
	v_cvt_pk_bf16_f32 v3, v4, v5
	v_cvt_pk_bf16_f32 v4, v6, v7
	s_nop 0
	v_cvt_pk_bf16_f32 v5, v8, v9
	global_store_dwordx4 v[22:23], v[2:5], off
	s_cbranch_vccnz .LBB0_1123
	s_andn2_b64 vcc, exec, s[10:11]
	s_cbranch_vccnz .LBB0_1122
	s_barrier
	s_branch .LBB0_1122

; #define LAS __attribute__((address_space(3)))
; __global__ void __launch_bounds__(NTHREADS, 2) fwd(Args a) {
;     extern __shared__ __attribute__((aligned(16))) unsigned char lds_raw[];
;     LAS unsigned char* lds = (LAS unsigned char*)lds_raw;
	.amdhsa_kernel _Z3fwd4Args
		.amdhsa_group_segment_fixed_size 16384
		.amdhsa_private_segment_fixed_size 0
		.amdhsa_kernarg_size 496
		.amdhsa_user_sgpr_count 2
		.amdhsa_user_sgpr_dispatch_ptr 0
		.amdhsa_user_sgpr_queue_ptr 0
		.amdhsa_user_sgpr_kernarg_segment_ptr 1
		.amdhsa_user_sgpr_dispatch_id 0
		.amdhsa_user_sgpr_kernarg_preload_length 0
		.amdhsa_user_sgpr_kernarg_preload_offset 0
		.amdhsa_user_sgpr_private_segment_size 0
		.amdhsa_uses_dynamic_stack 0
		.amdhsa_enable_private_segment 0
		.amdhsa_system_sgpr_workgroup_id_x 1
		.amdhsa_system_sgpr_workgroup_id_y 0
		.amdhsa_system_sgpr_workgroup_id_z 0
		.amdhsa_system_sgpr_workgroup_info 0
		.amdhsa_system_vgpr_workitem_id 0
		.amdhsa_next_free_vgpr 255
		.amdhsa_next_free_sgpr 102
		.amdhsa_accum_offset 256
		.amdhsa_reserve_vcc 1
		.amdhsa_float_round_mode_32 0
		.amdhsa_float_round_mode_16_64 0
		.amdhsa_float_denorm_mode_32 3
		.amdhsa_float_denorm_mode_16_64 3
		.amdhsa_dx10_clamp 1
		.amdhsa_ieee_mode 1
		.amdhsa_fp16_overflow 0
		.amdhsa_tg_split 0
		.amdhsa_exception_fp_ieee_invalid_op 0
		.amdhsa_exception_fp_denorm_src 0
		.amdhsa_exception_fp_ieee_div_zero 0
		.amdhsa_exception_fp_ieee_overflow 0
		.amdhsa_exception_fp_ieee_underflow 0
		.amdhsa_exception_fp_ieee_inexact 0
		.amdhsa_exception_int_div_zero 0
	.end_amdhsa_kernel

; #define LAS __attribute__((address_space(3)))
; __global__ void __launch_bounds__(NTHREADS, 2) fwd(Args a) {
;     extern __shared__ __attribute__((aligned(16))) unsigned char lds_raw[];
;     LAS unsigned char* lds = (LAS unsigned char*)lds_raw;
amdhsa.kernels:
  - .agpr_count:     0
    .args:
      - .offset:         0
        .size:           240
        .value_kind:     by_value
      - .offset:         240
        .size:           4
        .value_kind:     hidden_block_count_x
      - .offset:         244
        .size:           4
        .value_kind:     hidden_block_count_y
      - .offset:         248
        .size:           4
        .value_kind:     hidden_block_count_z
      - .offset:         252
        .size:           2
        .value_kind:     hidden_group_size_x
      - .offset:         254
        .size:           2
        .value_kind:     hidden_group_size_y
      - .offset:         256
        .size:           2
        .value_kind:     hidden_group_size_z
      - .offset:         258
        .size:           2
        .value_kind:     hidden_remainder_x
      - .offset:         260
        .size:           2
        .value_kind:     hidden_remainder_y
      - .offset:         262
        .size:           2
        .value_kind:     hidden_remainder_z
      - .offset:         280
        .size:           8
        .value_kind:     hidden_global_offset_x
      - .offset:         288
        .size:           8
        .value_kind:     hidden_global_offset_y
      - .offset:         296
        .size:           8
        .value_kind:     hidden_global_offset_z
      - .offset:         304
        .size:           2
        .value_kind:     hidden_grid_dims
      - .offset:         360
        .size:           4
        .value_kind:     hidden_dynamic_lds_size
    .group_segment_fixed_size: 16384
    .kernarg_segment_align: 8
    .kernarg_segment_size: 496
    .language:       OpenCL C
    .language_version:
      - 2
      - 0
    .max_flat_workgroup_size: 512
    .name:           _Z3fwd4Args
    .private_segment_fixed_size: 0
    .sgpr_count:     108
    .sgpr_spill_count: 64
    .symbol:         _Z3fwd4Args.kd
    .uniform_work_group_size: 1
    .uses_dynamic_stack: false
    .vgpr_count:     255
    .vgpr_spill_count: 0
    .wavefront_size: 64
